# GQA and MLA attention loops unrolled 2x with static LDS buffer parity: K/V LDS read addresses become immediates on precomputed address registers (address VALU removed from the per-tile critical path)
# speedup vs baseline: 1.1055x; 1.0150x over previous
.LBB0_119:
	s_mov_b32 s38, s10
	s_ashr_i32 s9, s8, 31
	s_lshl_b32 s11, s20, 9
	s_add_u32 s12, s14, s11
	s_addc_u32 s13, s15, 0
	s_ashr_i32 s11, s10, 31
	v_lshl_add_u64 v[2:3], s[10:11], 0, v[170:171]
	v_lshl_add_u64 v[6:7], v[174:175], 0, s[10:11]
	v_lshlrev_b64 v[22:23], 12, v[2:3]
	v_lshlrev_b64 v[6:7], 12, v[6:7]
	v_lshl_add_u64 v[10:11], s[10:11], 0, v[172:173]
	v_lshl_add_u64 v[2:3], s[12:13], 0, v[22:23]
	v_mov_b32_e32 v189, v1
	v_lshl_add_u64 v[6:7], s[12:13], 0, v[6:7]
	v_lshlrev_b64 v[24:25], 12, v[10:11]
	v_lshl_add_u64 v[14:15], v[2:3], 0, v[188:189]
	v_lshl_add_u64 v[18:19], v[6:7], 0, v[188:189]
	v_lshl_add_u64 v[10:11], v[176:177], 0, v[24:25]
	global_load_dwordx4 v[2:5], v[14:15], off
	global_load_dwordx4 v[6:9], v[18:19], off
	s_nop 0
	global_load_dwordx4 v[10:13], v[10:11], off
	s_nop 0
	global_load_dwordx4 v[14:17], v[14:15], off offset:256
	s_nop 0
	global_load_dwordx4 v[18:21], v[18:19], off offset:256
	v_add_u32_e32 v26, 16, v198
	s_waitcnt vmcnt(0)
	s_and_b32 s22, s18, 7
	v_lshl_or_b32 v22, s22, 9, v22
	s_lshl_b32 s10, s21, 18
	v_lshl_add_u64 v[192:193], v[184:185], 0, v[24:25]
	v_lshl_add_u64 v[194:195], v[186:187], 0, v[22:23]
	s_add_u32 s21, s10, 0x40000
	s_mov_b32 s22, 0
	v_mov_b32_e32 v234, 0
	v_mov_b32_e32 v189, 0xf149f2ca
	s_mov_b64 s[10:11], 0
	s_waitcnt vmcnt(0)
	ds_write_b128 v26, v[14:17]
	v_add_u32_e32 v14, 16, v199
	s_waitcnt vmcnt(0)
	ds_write_b128 v14, v[18:21]
	v_add_u32_e32 v14, 16, v200
	ds_write_b128 v14, v[2:5] offset:32768
	ds_write_b128 v14, v[6:9] offset:45056
	v_add_u32_e32 v2, 16, v201
	v_mov_b32_e32 v16, v1
	v_mov_b32_e32 v17, v1
	ds_write_b128 v2, v[10:13] offset:32768
	v_mov_b32_e32 v2, v1
	v_mov_b32_e32 v3, v1
	v_mov_b32_e32 v4, v1
	v_mov_b32_e32 v5, v1
	v_mov_b32_e32 v6, v1
	v_mov_b32_e32 v7, v1
	v_mov_b32_e32 v8, v1
	v_mov_b32_e32 v9, v1
	v_mov_b32_e32 v10, v1
	v_mov_b32_e32 v11, v1
	v_mov_b32_e32 v12, v1
	v_mov_b32_e32 v13, v1
	v_mov_b32_e32 v14, v1
	v_mov_b32_e32 v15, v1
	v_mov_b64_e32 v[32:33], v[16:17]
	v_mov_b64_e32 v[48:49], v[16:17]
	v_mov_b64_e32 v[64:65], v[16:17]
	v_mov_b64_e32 v[30:31], v[14:15]
	v_mov_b64_e32 v[28:29], v[12:13]
	v_mov_b64_e32 v[26:27], v[10:11]
	v_mov_b64_e32 v[24:25], v[8:9]
	v_mov_b64_e32 v[22:23], v[6:7]
	v_mov_b64_e32 v[20:21], v[4:5]
	v_mov_b64_e32 v[18:19], v[2:3]
	v_mov_b64_e32 v[46:47], v[14:15]
	v_mov_b64_e32 v[44:45], v[12:13]
	v_mov_b64_e32 v[42:43], v[10:11]
	v_mov_b64_e32 v[40:41], v[8:9]
	v_mov_b64_e32 v[38:39], v[6:7]
	v_mov_b64_e32 v[36:37], v[4:5]
	v_mov_b64_e32 v[34:35], v[2:3]
	v_mov_b64_e32 v[62:63], v[14:15]
	v_mov_b64_e32 v[60:61], v[12:13]
	v_mov_b64_e32 v[58:59], v[10:11]
	v_mov_b64_e32 v[56:57], v[8:9]
	v_mov_b64_e32 v[54:55], v[6:7]
	v_mov_b64_e32 v[52:53], v[4:5]
	v_mov_b64_e32 v[50:51], v[2:3]
	s_waitcnt lgkmcnt(0)
	s_barrier
	s_lshl_b32 s12, s20, 9
	s_add_i32 s12, s12, 0x8400000
	v_and_b32_e32 v66, 63, v178
	v_lshrrev_b32_e32 v67, 6, v178
	v_mul_u32_u24_e32 v68, 0xc0, v67
	v_add_u32_e32 v68, v68, v66
	v_mul_u32_u24_e32 v70, 0xaab, v68
	v_lshrrev_b32_e32 v70, 16, v70
	v_mul_u32_u24_e32 v71, 24, v70
	v_sub_u32_e32 v71, v68, v71
	v_and_b32_e32 v72, 15, v70
	v_xor_b32_e32 v72, v71, v72
	v_lshlrev_b32_e32 v72, 4, v72
	v_add_u32_e32 v72, s12, v72
	v_add_u32_e32 v73, -16, v71
	v_and_b32_e32 v74, 7, v70
	v_xor_b32_e32 v73, v73, v74
	v_lshlrev_b32_e32 v73, 4, v73
	v_add_u32_e32 v73, 0x600, v73
	v_cmp_gt_u32_e32 vcc, 16, v71
	s_nop 1
	v_cndmask_b32_e32 v72, v73, v72, vcc
	v_lshl_add_u32 v146, v70, 12, v72
	v_add_u32_e32 v68, 64, v68
	v_mul_u32_u24_e32 v70, 0xaab, v68
	v_lshrrev_b32_e32 v70, 16, v70
	v_mul_u32_u24_e32 v71, 24, v70
	v_sub_u32_e32 v71, v68, v71
	v_and_b32_e32 v72, 15, v70
	v_xor_b32_e32 v72, v71, v72
	v_lshlrev_b32_e32 v72, 4, v72
	v_add_u32_e32 v72, s12, v72
	v_add_u32_e32 v73, -16, v71
	v_and_b32_e32 v74, 7, v70
	v_xor_b32_e32 v73, v73, v74
	v_lshlrev_b32_e32 v73, 4, v73
	v_add_u32_e32 v73, 0x600, v73
	v_cmp_gt_u32_e32 vcc, 16, v71
	s_nop 1
	v_cndmask_b32_e32 v72, v73, v72, vcc
	v_lshl_add_u32 v147, v70, 12, v72
	v_add_u32_e32 v68, 64, v68
	v_mul_u32_u24_e32 v70, 0xaab, v68
	v_lshrrev_b32_e32 v70, 16, v70
	v_mul_u32_u24_e32 v71, 24, v70
	v_sub_u32_e32 v71, v68, v71
	v_and_b32_e32 v72, 15, v70
	v_xor_b32_e32 v72, v71, v72
	v_lshlrev_b32_e32 v72, 4, v72
	v_add_u32_e32 v72, s12, v72
	v_add_u32_e32 v73, -16, v71
	v_and_b32_e32 v74, 7, v70
	v_xor_b32_e32 v73, v73, v74
	v_lshlrev_b32_e32 v73, 4, v73
	v_add_u32_e32 v73, 0x600, v73
	v_cmp_gt_u32_e32 vcc, 16, v71
	s_nop 1
	v_cndmask_b32_e32 v72, v73, v72, vcc
	v_lshl_add_u32 v148, v70, 12, v72
	v_and_b32_e32 v70, 31, v66
	v_lshrrev_b32_e32 v70, 2, v70
	v_lshl_add_u32 v70, v67, 3, v70
	v_lshrrev_b32_e32 v71, 5, v66
	v_lshlrev_b32_e32 v71, 6, v71
	v_and_b32_e32 v72, 3, v66
	v_lshlrev_b32_e32 v72, 4, v72
	v_add3_u32 v71, v71, v72, s12
	v_add_u32_e32 v71, 0x100, v71
	v_lshl_add_u32 v149, v70, 12, v71
	v_add_u32_e32 v150, 0x80, v149
	s_add_i32 s24, s38, 64
	s_lshl_b32 s24, s24, 12
	s_add_u32 s24, s24, 0x4600000
	s_add_u32 s24, s98, s24
	s_addc_u32 s25, s99, 0
	v_readlane_b32 s26, v254, 10
	s_nop 3
	s_lshr_b32 s36, s26, 6
	s_lshl_b32 s26, s26, 5
	s_add_i32 s26, s26, 16
	s_mul_i32 s36, s36, 0xc00
	s_add_i32 s36, s36, 0x8010
	s_movk_i32 s12, 0x2000
	v_add3_u32 v151, v203, v220, s12
	v_add3_u32 v152, v203, v221, s12
	v_add3_u32 v153, v203, v222, s12
	v_add3_u32 v154, v203, v223, s12
	v_add3_u32 v155, v203, v224, s12
	v_add3_u32 v156, v203, v225, s12
	v_add3_u32 v157, v203, v226, s12
	v_add3_u32 v158, v203, v227, s12
	v_add3_u32 v159, v203, v228, s12
	v_add3_u32 v160, v203, v229, s12
	v_add3_u32 v161, v203, v230, s12
	v_add3_u32 v162, v203, v231, s12
	s_branch .Lmu_b120
.Lmu_a120:
	ds_read_b128 v[66:69], v151 offset:49152
	ds_read_b128 v[70:73], v151 offset:61440
	ds_read_b128 v[236:239], v152 offset:49152
	ds_read_b128 v[240:243], v152 offset:61440
	s_waitcnt lgkmcnt(3)
	v_mfma_f32_32x32x16_bf16 v[82:97], v[66:69], v[134:137], 0
	s_waitcnt lgkmcnt(2)
	v_mfma_f32_32x32x16_bf16 v[66:81], v[70:73], v[134:137], 0
	s_waitcnt lgkmcnt(1)
	v_mfma_f32_32x32x16_bf16 v[82:97], v[236:239], v[130:133], v[82:97]
	s_waitcnt lgkmcnt(0)
	v_mfma_f32_32x32x16_bf16 v[66:81], v[240:243], v[130:133], v[66:81]
	ds_read_b128 v[236:239], v153 offset:49152
	ds_read_b128 v[240:243], v153 offset:61440
	s_waitcnt lgkmcnt(1)
	v_mfma_f32_32x32x16_bf16 v[82:97], v[236:239], v[126:129], v[82:97]
	s_waitcnt lgkmcnt(0)
	v_mfma_f32_32x32x16_bf16 v[66:81], v[240:243], v[126:129], v[66:81]
	ds_read_b128 v[236:239], v154 offset:49152
	ds_read_b128 v[240:243], v154 offset:61440
	s_waitcnt lgkmcnt(1)
	v_mfma_f32_32x32x16_bf16 v[82:97], v[236:239], v[122:125], v[82:97]
	s_waitcnt lgkmcnt(0)
	v_mfma_f32_32x32x16_bf16 v[66:81], v[240:243], v[122:125], v[66:81]
	ds_read_b128 v[236:239], v155 offset:49152
	ds_read_b128 v[240:243], v155 offset:61440
	s_waitcnt lgkmcnt(1)
	v_mfma_f32_32x32x16_bf16 v[82:97], v[236:239], v[118:121], v[82:97]
	s_waitcnt lgkmcnt(0)
	v_mfma_f32_32x32x16_bf16 v[66:81], v[240:243], v[118:121], v[66:81]
	ds_read_b128 v[236:239], v156 offset:49152
	ds_read_b128 v[240:243], v156 offset:61440
	s_waitcnt lgkmcnt(1)
	v_mfma_f32_32x32x16_bf16 v[82:97], v[236:239], v[114:117], v[82:97]
	s_waitcnt lgkmcnt(0)
	v_mfma_f32_32x32x16_bf16 v[66:81], v[240:243], v[114:117], v[66:81]
	ds_read_b128 v[236:239], v157 offset:49152
	ds_read_b128 v[240:243], v157 offset:61440
	s_waitcnt lgkmcnt(1)
	v_mfma_f32_32x32x16_bf16 v[82:97], v[236:239], v[110:113], v[82:97]
	s_waitcnt lgkmcnt(0)
	v_mfma_f32_32x32x16_bf16 v[66:81], v[240:243], v[110:113], v[66:81]
	ds_read_b128 v[236:239], v158 offset:49152
	ds_read_b128 v[240:243], v158 offset:61440
	s_waitcnt lgkmcnt(1)
	v_mfma_f32_32x32x16_bf16 v[82:97], v[236:239], v[106:109], v[82:97]
	s_waitcnt lgkmcnt(0)
	v_mfma_f32_32x32x16_bf16 v[66:81], v[240:243], v[106:109], v[66:81]
	ds_read_b128 v[236:239], v159 offset:49152
	ds_read_b128 v[240:243], v159 offset:61440
	s_waitcnt lgkmcnt(1)
	v_mfma_f32_32x32x16_bf16 v[82:97], v[236:239], v[102:105], v[82:97]
	s_waitcnt lgkmcnt(0)
	v_mfma_f32_32x32x16_bf16 v[66:81], v[240:243], v[102:105], v[66:81]
	ds_read_b128 v[236:239], v160 offset:49152
	ds_read_b128 v[240:243], v160 offset:61440
	s_waitcnt lgkmcnt(1)
	v_mfma_f32_32x32x16_bf16 v[82:97], v[236:239], v[98:101], v[82:97]
	s_waitcnt lgkmcnt(0)
	v_mfma_f32_32x32x16_bf16 v[66:81], v[240:243], v[98:101], v[66:81]
	ds_read_b128 v[236:239], v161 offset:49152
	ds_read_b128 v[240:243], v161 offset:61440
	s_waitcnt lgkmcnt(1)
	v_mfma_f32_32x32x16_bf16 v[82:97], v[236:239], v[138:141], v[82:97]
	s_waitcnt lgkmcnt(0)
	v_mfma_f32_32x32x16_bf16 v[66:81], v[240:243], v[138:141], v[66:81]
	ds_read_b128 v[236:239], v162 offset:49152
	ds_read_b128 v[240:243], v162 offset:61440
	s_waitcnt lgkmcnt(1)
	v_mfma_f32_32x32x16_bf16 v[82:97], v[236:239], v[142:145], v[82:97]
	s_waitcnt lgkmcnt(0)
	v_mfma_f32_32x32x16_bf16 v[66:81], v[240:243], v[142:145], v[66:81]
	s_mov_b32 m0, s26
	s_nop 0
	global_load_lds_dwordx4 v149, s[24:25]
	s_add_i32 m0, s26, 0x400
	s_nop 0
	global_load_lds_dwordx4 v150, s[24:25]
	s_mov_b32 m0, s36
	s_nop 0
	global_load_lds_dwordx4 v146, s[24:25]
	s_add_i32 m0, s36, 0x400
	s_nop 0
	global_load_lds_dwordx4 v147, s[24:25]
	s_add_i32 m0, s36, 0x800
	s_nop 0
	global_load_lds_dwordx4 v148, s[24:25]
	s_add_u32 s24, s24, 0x40000
	s_addc_u32 s25, s25, 0
	s_nop 1
	v_max_f32_e32 v191, v83, v83
	v_max_f32_e32 v235, v82, v82
	v_max_f32_e32 v191, v235, v191
	v_max3_f32 v191, v191, v84, v85
	v_max3_f32 v191, v191, v86, v87
	v_max3_f32 v191, v191, v88, v89
	v_max3_f32 v191, v191, v90, v91
	v_max3_f32 v191, v191, v92, v93
	v_max3_f32 v191, v191, v94, v95
	v_max3_f32 v191, v191, v96, v97
	v_max3_f32 v191, v191, v66, v67
	v_max3_f32 v191, v191, v68, v69
	v_max3_f32 v191, v191, v70, v71
	v_max3_f32 v191, v191, v72, v73
	v_max3_f32 v191, v191, v74, v75
	v_max3_f32 v191, v191, v76, v77
	v_max3_f32 v191, v191, v78, v79
	v_max3_f32 v191, v191, v80, v81
	v_mov_b32_e32 v235, v191
	s_nop 1
	v_permlane32_swap_b32_e32 v191, v235
	v_max_f32_e32 v235, v235, v235
	v_max_f32_e32 v191, v191, v191
	v_max_f32_e32 v191, v191, v235
	v_sub_f32_e32 v235, v191, v189
	v_cmp_ge_f32_e32 vcc, s56, v235
	s_cmp_eq_u64 vcc, exec
	v_max_f32_e32 v235, v189, v189
	s_cselect_b64 vcc, -1, 0
	v_max_f32_e32 v191, v235, v191
	v_sub_f32_e32 v235, v189, v191
	v_cndmask_b32_e32 v189, v191, v189, vcc
	v_mul_f32_e32 v191, 0xbdd53b94, v189
	v_fmamk_f32 v82, v82, 0x3dd53b94, v191
	v_fmamk_f32 v83, v83, 0x3dd53b94, v191
	v_fmamk_f32 v84, v84, 0x3dd53b94, v191
	v_fmamk_f32 v85, v85, 0x3dd53b94, v191
	v_fmamk_f32 v86, v86, 0x3dd53b94, v191
	v_fmamk_f32 v87, v87, 0x3dd53b94, v191
	v_fmamk_f32 v88, v88, 0x3dd53b94, v191
	v_fmamk_f32 v89, v89, 0x3dd53b94, v191
	v_fmamk_f32 v90, v90, 0x3dd53b94, v191
	v_fmamk_f32 v91, v91, 0x3dd53b94, v191
	v_fmamk_f32 v92, v92, 0x3dd53b94, v191
	v_fmamk_f32 v93, v93, 0x3dd53b94, v191
	v_fmamk_f32 v94, v94, 0x3dd53b94, v191
	v_fmamk_f32 v95, v95, 0x3dd53b94, v191
	v_fmamk_f32 v96, v96, 0x3dd53b94, v191
	v_fmamk_f32 v97, v97, 0x3dd53b94, v191
	v_fmamk_f32 v66, v66, 0x3dd53b94, v191
	v_fmamk_f32 v67, v67, 0x3dd53b94, v191
	v_fmamk_f32 v68, v68, 0x3dd53b94, v191
	v_fmamk_f32 v69, v69, 0x3dd53b94, v191
	v_fmamk_f32 v70, v70, 0x3dd53b94, v191
	v_fmamk_f32 v71, v71, 0x3dd53b94, v191
	v_fmamk_f32 v72, v72, 0x3dd53b94, v191
	v_fmamk_f32 v73, v73, 0x3dd53b94, v191
	v_fmamk_f32 v74, v74, 0x3dd53b94, v191
	v_fmamk_f32 v75, v75, 0x3dd53b94, v191
	v_fmamk_f32 v76, v76, 0x3dd53b94, v191
	v_fmamk_f32 v77, v77, 0x3dd53b94, v191
	v_fmamk_f32 v78, v78, 0x3dd53b94, v191
	v_fmamk_f32 v79, v79, 0x3dd53b94, v191
	v_fmamk_f32 v80, v80, 0x3dd53b94, v191
	v_fmac_f32_e32 v191, 0x3dd53b94, v81
	v_exp_f32_e32 v81, v82
	v_exp_f32_e32 v236, v83
	v_exp_f32_e32 v84, v84
	v_exp_f32_e32 v85, v85
	v_exp_f32_e32 v86, v86
	v_exp_f32_e32 v237, v70
	v_add_f32_e32 v70, 0, v81
	v_exp_f32_e32 v87, v87
	v_add_f32_e32 v70, v236, v70
	v_exp_f32_e32 v88, v88
	v_add_f32_e32 v70, v84, v70
	v_exp_f32_e32 v89, v89
	v_add_f32_e32 v70, v85, v70
	v_exp_f32_e32 v90, v90
	v_add_f32_e32 v70, v86, v70
	v_exp_f32_e32 v91, v91
	v_add_f32_e32 v70, v87, v70
	v_exp_f32_e32 v92, v92
	v_add_f32_e32 v70, v88, v70
	v_exp_f32_e32 v93, v93
	v_add_f32_e32 v70, v89, v70
	v_exp_f32_e32 v94, v94
	v_add_f32_e32 v70, v90, v70
	v_exp_f32_e32 v95, v95
	v_add_f32_e32 v70, v91, v70
	v_exp_f32_e32 v96, v96
	v_add_f32_e32 v70, v92, v70
	v_exp_f32_e32 v97, v97
	v_add_f32_e32 v70, v93, v70
	v_exp_f32_e32 v66, v66
	v_add_f32_e32 v70, v94, v70
	v_exp_f32_e32 v67, v67
	v_add_f32_e32 v70, v95, v70
	v_exp_f32_e32 v68, v68
	v_add_f32_e32 v70, v96, v70
	v_exp_f32_e32 v69, v69
	v_add_f32_e32 v70, v97, v70
	v_add_f32_e32 v70, v66, v70
	v_exp_f32_e32 v238, v71
	v_add_f32_e32 v70, v67, v70
	v_exp_f32_e32 v239, v72
	v_add_f32_e32 v70, v68, v70
	v_exp_f32_e32 v73, v73
	v_add_f32_e32 v70, v69, v70
	v_exp_f32_e32 v240, v74
	v_add_f32_e32 v70, v237, v70
	v_exp_f32_e32 v241, v75
	v_add_f32_e32 v70, v238, v70
	v_exp_f32_e32 v242, v76
	v_add_f32_e32 v70, v239, v70
	v_exp_f32_e32 v243, v77
	v_add_f32_e32 v70, v73, v70
	v_exp_f32_e32 v244, v78
	v_add_f32_e32 v70, v240, v70
	v_exp_f32_e32 v245, v79
	v_add_f32_e32 v70, v241, v70
	v_exp_f32_e32 v246, v80
	v_add_f32_e32 v70, v242, v70
	v_mul_f32_e32 v235, 0x3dd53b94, v235
	v_exp_f32_e32 v191, v191
	v_add_f32_e32 v70, v243, v70
	v_exp_f32_e32 v235, v235
	v_add_f32_e32 v70, v244, v70
	v_add_f32_e32 v70, v245, v70
	v_add_f32_e32 v70, v246, v70
	v_add_f32_e32 v82, v191, v70
	v_cndmask_b32_e64 v235, v235, 1.0, vcc
	v_mov_b32_e32 v83, v82
	s_nop 1
	v_permlane32_swap_b32_e32 v82, v83
	v_cmp_gt_f32_e32 vcc, 1.0, v235
	v_cvt_pk_bf16_f32 v78, v81, v236
	v_cvt_pk_bf16_f32 v79, v84, v85
	v_cvt_pk_bf16_f32 v80, v86, v87
	v_cvt_pk_bf16_f32 v81, v88, v89
	v_cvt_pk_bf16_f32 v74, v90, v91
	v_cvt_pk_bf16_f32 v75, v92, v93
	v_cvt_pk_bf16_f32 v76, v94, v95
	v_cvt_pk_bf16_f32 v77, v96, v97
	v_cvt_pk_bf16_f32 v70, v66, v67
	v_cvt_pk_bf16_f32 v71, v68, v69
	v_cvt_pk_bf16_f32 v72, v237, v238
	v_cvt_pk_bf16_f32 v73, v239, v73
	v_cvt_pk_bf16_f32 v66, v240, v241
	v_cvt_pk_bf16_f32 v67, v242, v243
	v_cvt_pk_bf16_f32 v68, v244, v245
	v_cvt_pk_bf16_f32 v69, v246, v191
	s_cbranch_vccz .Lmu_a124
	s_and_saveexec_b64 s[12:13], s[4:5]
	ds_write_b32 v232, v235 offset:128
	s_or_b64 exec, exec, s[12:13]
	s_waitcnt lgkmcnt(0)
	v_add_u32_e32 v96, v196, v202
	ds_read_b128 v[84:87], v96 offset:224
	ds_read_b128 v[88:91], v96 offset:192
	ds_read_b128 v[92:95], v96 offset:160
	ds_read_b128 v[236:239], v96 offset:128
	s_waitcnt lgkmcnt(3)
	v_pk_mul_f32 v[14:15], v[14:15], v[84:85]
	s_waitcnt lgkmcnt(2)
	v_pk_mul_f32 v[10:11], v[10:11], v[88:89]
	s_waitcnt lgkmcnt(1)
	v_pk_mul_f32 v[6:7], v[6:7], v[92:93]
	v_pk_mul_f32 v[16:17], v[16:17], v[86:87]
	v_pk_mul_f32 v[12:13], v[12:13], v[90:91]
	v_pk_mul_f32 v[8:9], v[8:9], v[94:95]
	s_waitcnt lgkmcnt(0)
	v_pk_mul_f32 v[4:5], v[4:5], v[238:239]
	v_pk_mul_f32 v[2:3], v[2:3], v[236:237]
	v_pk_mul_f32 v[30:31], v[30:31], v[84:85]
	v_pk_mul_f32 v[26:27], v[26:27], v[88:89]
	v_pk_mul_f32 v[22:23], v[22:23], v[92:93]
	v_pk_mul_f32 v[32:33], v[32:33], v[86:87]
	v_pk_mul_f32 v[28:29], v[28:29], v[90:91]
	v_pk_mul_f32 v[24:25], v[24:25], v[94:95]
	v_pk_mul_f32 v[20:21], v[20:21], v[238:239]
	v_pk_mul_f32 v[18:19], v[18:19], v[236:237]
	v_pk_mul_f32 v[46:47], v[46:47], v[84:85]
	v_pk_mul_f32 v[42:43], v[42:43], v[88:89]
	v_pk_mul_f32 v[38:39], v[38:39], v[92:93]
	v_pk_mul_f32 v[48:49], v[48:49], v[86:87]
	v_pk_mul_f32 v[44:45], v[44:45], v[90:91]
	v_pk_mul_f32 v[40:41], v[40:41], v[94:95]
	v_pk_mul_f32 v[36:37], v[36:37], v[238:239]
	v_pk_mul_f32 v[34:35], v[34:35], v[236:237]
	v_pk_mul_f32 v[62:63], v[62:63], v[84:85]
	v_pk_mul_f32 v[58:59], v[58:59], v[88:89]
	v_pk_mul_f32 v[54:55], v[54:55], v[92:93]
	v_pk_mul_f32 v[64:65], v[64:65], v[86:87]
	v_pk_mul_f32 v[60:61], v[60:61], v[90:91]
	v_pk_mul_f32 v[56:57], v[56:57], v[94:95]
	v_pk_mul_f32 v[52:53], v[52:53], v[238:239]
	v_pk_mul_f32 v[50:51], v[50:51], v[236:237]
.Lmu_a124:
	v_add_f32_e32 v191, v82, v83
	v_fmac_f32_e32 v191, v234, v235
	ds_read_b64_tr_b16 v[82:83], v233 offset:16384
	ds_read_b64_tr_b16 v[84:85], v233 offset:18432
	ds_read_b64_tr_b16 v[86:87], v233 offset:20480
	ds_read_b64_tr_b16 v[88:89], v233 offset:22528
	ds_read_b64_tr_b16 v[90:91], v233 offset:24576
	ds_read_b64_tr_b16 v[92:93], v233 offset:26624
	ds_read_b64_tr_b16 v[94:95], v233 offset:28672
	ds_read_b64_tr_b16 v[96:97], v233 offset:30720
	s_waitcnt lgkmcnt(0)
	s_nop 0
	v_mfma_f32_32x32x16_bf16 v[2:17], v[78:81], v[82:85], v[2:17]
	ds_read_b64_tr_b16 v[82:83], v233 offset:16896
	ds_read_b64_tr_b16 v[84:85], v233 offset:18944
	v_mfma_f32_32x32x16_bf16 v[2:17], v[74:77], v[86:89], v[2:17]
	ds_read_b64_tr_b16 v[86:87], v233 offset:20992
	ds_read_b64_tr_b16 v[88:89], v233 offset:23040
	v_mfma_f32_32x32x16_bf16 v[2:17], v[70:73], v[90:93], v[2:17]
	ds_read_b64_tr_b16 v[90:91], v233 offset:25088
	ds_read_b64_tr_b16 v[92:93], v233 offset:27136
	v_mfma_f32_32x32x16_bf16 v[2:17], v[66:69], v[94:97], v[2:17]
	ds_read_b64_tr_b16 v[94:95], v233 offset:29184
	ds_read_b64_tr_b16 v[96:97], v233 offset:31232
	s_waitcnt lgkmcnt(0)
	v_mfma_f32_32x32x16_bf16 v[18:33], v[78:81], v[82:85], v[18:33]
	ds_read_b64_tr_b16 v[82:83], v233 offset:17408
	ds_read_b64_tr_b16 v[84:85], v233 offset:19456
	v_mfma_f32_32x32x16_bf16 v[18:33], v[74:77], v[86:89], v[18:33]
	ds_read_b64_tr_b16 v[86:87], v233 offset:21504
	ds_read_b64_tr_b16 v[88:89], v233 offset:23552
	v_mfma_f32_32x32x16_bf16 v[18:33], v[70:73], v[90:93], v[18:33]
	ds_read_b64_tr_b16 v[90:91], v233 offset:25600
	ds_read_b64_tr_b16 v[92:93], v233 offset:27648
	v_mfma_f32_32x32x16_bf16 v[18:33], v[66:69], v[94:97], v[18:33]
	ds_read_b64_tr_b16 v[94:95], v233 offset:29696
	ds_read_b64_tr_b16 v[96:97], v233 offset:31744
	s_waitcnt lgkmcnt(0)
	v_mfma_f32_32x32x16_bf16 v[34:49], v[78:81], v[82:85], v[34:49]
	ds_read_b64_tr_b16 v[82:83], v233 offset:17920
	ds_read_b64_tr_b16 v[84:85], v233 offset:19968
	v_mfma_f32_32x32x16_bf16 v[34:49], v[74:77], v[86:89], v[34:49]
	ds_read_b64_tr_b16 v[86:87], v233 offset:22016
	ds_read_b64_tr_b16 v[88:89], v233 offset:24064
	v_mfma_f32_32x32x16_bf16 v[34:49], v[70:73], v[90:93], v[34:49]
	ds_read_b64_tr_b16 v[90:91], v233 offset:26112
	ds_read_b64_tr_b16 v[92:93], v233 offset:28160
	v_mfma_f32_32x32x16_bf16 v[34:49], v[66:69], v[94:97], v[34:49]
	ds_read_b64_tr_b16 v[94:95], v233 offset:30208
	ds_read_b64_tr_b16 v[96:97], v233 offset:32256
	s_waitcnt lgkmcnt(0)
	v_mfma_f32_32x32x16_bf16 v[50:65], v[78:81], v[82:85], v[50:65]
	v_mfma_f32_32x32x16_bf16 v[50:65], v[74:77], v[86:89], v[50:65]
	s_add_u32 s10, s10, 0x40000
	s_addc_u32 s11, s11, 0
	s_add_i32 s22, s22, 1
	s_cmp_eq_u32 s21, s10
	v_mfma_f32_32x32x16_bf16 v[50:65], v[70:73], v[90:93], v[50:65]
	s_waitcnt vmcnt(0)
	s_barrier
	v_mfma_f32_32x32x16_bf16 v[50:65], v[66:69], v[94:97], v[50:65]
	v_mov_b32_e32 v234, v191
.Lmu_b120:
	ds_read_b128 v[66:69], v151 offset:24576
	ds_read_b128 v[70:73], v151 offset:36864
	ds_read_b128 v[236:239], v152 offset:24576
	ds_read_b128 v[240:243], v152 offset:36864
	s_waitcnt lgkmcnt(3)
	v_mfma_f32_32x32x16_bf16 v[82:97], v[66:69], v[134:137], 0
	s_waitcnt lgkmcnt(2)
	v_mfma_f32_32x32x16_bf16 v[66:81], v[70:73], v[134:137], 0
	s_waitcnt lgkmcnt(1)
	v_mfma_f32_32x32x16_bf16 v[82:97], v[236:239], v[130:133], v[82:97]
	s_waitcnt lgkmcnt(0)
	v_mfma_f32_32x32x16_bf16 v[66:81], v[240:243], v[130:133], v[66:81]
	ds_read_b128 v[236:239], v153 offset:24576
	ds_read_b128 v[240:243], v153 offset:36864
	s_waitcnt lgkmcnt(1)
	v_mfma_f32_32x32x16_bf16 v[82:97], v[236:239], v[126:129], v[82:97]
	s_waitcnt lgkmcnt(0)
	v_mfma_f32_32x32x16_bf16 v[66:81], v[240:243], v[126:129], v[66:81]
	ds_read_b128 v[236:239], v154 offset:24576
	ds_read_b128 v[240:243], v154 offset:36864
	s_waitcnt lgkmcnt(1)
	v_mfma_f32_32x32x16_bf16 v[82:97], v[236:239], v[122:125], v[82:97]
	s_waitcnt lgkmcnt(0)
	v_mfma_f32_32x32x16_bf16 v[66:81], v[240:243], v[122:125], v[66:81]
	ds_read_b128 v[236:239], v155 offset:24576
	ds_read_b128 v[240:243], v155 offset:36864
	s_waitcnt lgkmcnt(1)
	v_mfma_f32_32x32x16_bf16 v[82:97], v[236:239], v[118:121], v[82:97]
	s_waitcnt lgkmcnt(0)
	v_mfma_f32_32x32x16_bf16 v[66:81], v[240:243], v[118:121], v[66:81]
	ds_read_b128 v[236:239], v156 offset:24576
	ds_read_b128 v[240:243], v156 offset:36864
	s_waitcnt lgkmcnt(1)
	v_mfma_f32_32x32x16_bf16 v[82:97], v[236:239], v[114:117], v[82:97]
	s_waitcnt lgkmcnt(0)
	v_mfma_f32_32x32x16_bf16 v[66:81], v[240:243], v[114:117], v[66:81]
	ds_read_b128 v[236:239], v157 offset:24576
	ds_read_b128 v[240:243], v157 offset:36864
	s_waitcnt lgkmcnt(1)
	v_mfma_f32_32x32x16_bf16 v[82:97], v[236:239], v[110:113], v[82:97]
	s_waitcnt lgkmcnt(0)
	v_mfma_f32_32x32x16_bf16 v[66:81], v[240:243], v[110:113], v[66:81]
	ds_read_b128 v[236:239], v158 offset:24576
	ds_read_b128 v[240:243], v158 offset:36864
	s_waitcnt lgkmcnt(1)
	v_mfma_f32_32x32x16_bf16 v[82:97], v[236:239], v[106:109], v[82:97]
	s_waitcnt lgkmcnt(0)
	v_mfma_f32_32x32x16_bf16 v[66:81], v[240:243], v[106:109], v[66:81]
	ds_read_b128 v[236:239], v159 offset:24576
	ds_read_b128 v[240:243], v159 offset:36864
	s_waitcnt lgkmcnt(1)
	v_mfma_f32_32x32x16_bf16 v[82:97], v[236:239], v[102:105], v[82:97]
	s_waitcnt lgkmcnt(0)
	v_mfma_f32_32x32x16_bf16 v[66:81], v[240:243], v[102:105], v[66:81]
	ds_read_b128 v[236:239], v160 offset:24576
	ds_read_b128 v[240:243], v160 offset:36864
	s_waitcnt lgkmcnt(1)
	v_mfma_f32_32x32x16_bf16 v[82:97], v[236:239], v[98:101], v[82:97]
	s_waitcnt lgkmcnt(0)
	v_mfma_f32_32x32x16_bf16 v[66:81], v[240:243], v[98:101], v[66:81]
	ds_read_b128 v[236:239], v161 offset:24576
	ds_read_b128 v[240:243], v161 offset:36864
	s_waitcnt lgkmcnt(1)
	v_mfma_f32_32x32x16_bf16 v[82:97], v[236:239], v[138:141], v[82:97]
	s_waitcnt lgkmcnt(0)
	v_mfma_f32_32x32x16_bf16 v[66:81], v[240:243], v[138:141], v[66:81]
	ds_read_b128 v[236:239], v162 offset:24576
	ds_read_b128 v[240:243], v162 offset:36864
	s_waitcnt lgkmcnt(1)
	v_mfma_f32_32x32x16_bf16 v[82:97], v[236:239], v[142:145], v[82:97]
	s_waitcnt lgkmcnt(0)
	v_mfma_f32_32x32x16_bf16 v[66:81], v[240:243], v[142:145], v[66:81]
	s_add_i32 m0, s26, 0x4000
	s_nop 0
	global_load_lds_dwordx4 v149, s[24:25]
	s_add_i32 m0, s26, 0x4400
	s_nop 0
	global_load_lds_dwordx4 v150, s[24:25]
	s_add_i32 m0, s36, 0x6000
	s_nop 0
	global_load_lds_dwordx4 v146, s[24:25]
	s_add_i32 m0, s36, 0x6400
	s_nop 0
	global_load_lds_dwordx4 v147, s[24:25]
	s_add_i32 m0, s36, 0x6800
	s_nop 0
	global_load_lds_dwordx4 v148, s[24:25]
	s_add_u32 s24, s24, 0x40000
	s_addc_u32 s25, s25, 0
	s_nop 1
	v_max_f32_e32 v191, v83, v83
	v_max_f32_e32 v235, v82, v82
	v_max_f32_e32 v191, v235, v191
	v_max3_f32 v191, v191, v84, v85
	v_max3_f32 v191, v191, v86, v87
	v_max3_f32 v191, v191, v88, v89
	v_max3_f32 v191, v191, v90, v91
	v_max3_f32 v191, v191, v92, v93
	v_max3_f32 v191, v191, v94, v95
	v_max3_f32 v191, v191, v96, v97
	v_max3_f32 v191, v191, v66, v67
	v_max3_f32 v191, v191, v68, v69
	v_max3_f32 v191, v191, v70, v71
	v_max3_f32 v191, v191, v72, v73
	v_max3_f32 v191, v191, v74, v75
	v_max3_f32 v191, v191, v76, v77
	v_max3_f32 v191, v191, v78, v79
	v_max3_f32 v191, v191, v80, v81
	v_mov_b32_e32 v235, v191
	s_nop 1
	v_permlane32_swap_b32_e32 v191, v235
	v_max_f32_e32 v235, v235, v235
	v_max_f32_e32 v191, v191, v191
	v_max_f32_e32 v191, v191, v235
	v_sub_f32_e32 v235, v191, v189
	v_cmp_ge_f32_e32 vcc, s56, v235
	s_cmp_eq_u64 vcc, exec
	v_max_f32_e32 v235, v189, v189
	s_cselect_b64 vcc, -1, 0
	v_max_f32_e32 v191, v235, v191
	v_sub_f32_e32 v235, v189, v191
	v_cndmask_b32_e32 v189, v191, v189, vcc
	v_mul_f32_e32 v191, 0xbdd53b94, v189
	v_fmamk_f32 v82, v82, 0x3dd53b94, v191
	v_fmamk_f32 v83, v83, 0x3dd53b94, v191
	v_fmamk_f32 v84, v84, 0x3dd53b94, v191
	v_fmamk_f32 v85, v85, 0x3dd53b94, v191
	v_fmamk_f32 v86, v86, 0x3dd53b94, v191
	v_fmamk_f32 v87, v87, 0x3dd53b94, v191
	v_fmamk_f32 v88, v88, 0x3dd53b94, v191
	v_fmamk_f32 v89, v89, 0x3dd53b94, v191
	v_fmamk_f32 v90, v90, 0x3dd53b94, v191
	v_fmamk_f32 v91, v91, 0x3dd53b94, v191
	v_fmamk_f32 v92, v92, 0x3dd53b94, v191
	v_fmamk_f32 v93, v93, 0x3dd53b94, v191
	v_fmamk_f32 v94, v94, 0x3dd53b94, v191
	v_fmamk_f32 v95, v95, 0x3dd53b94, v191
	v_fmamk_f32 v96, v96, 0x3dd53b94, v191
	v_fmamk_f32 v97, v97, 0x3dd53b94, v191
	v_fmamk_f32 v66, v66, 0x3dd53b94, v191
	v_fmamk_f32 v67, v67, 0x3dd53b94, v191
	v_fmamk_f32 v68, v68, 0x3dd53b94, v191
	v_fmamk_f32 v69, v69, 0x3dd53b94, v191
	v_fmamk_f32 v70, v70, 0x3dd53b94, v191
	v_fmamk_f32 v71, v71, 0x3dd53b94, v191
	v_fmamk_f32 v72, v72, 0x3dd53b94, v191
	v_fmamk_f32 v73, v73, 0x3dd53b94, v191
	v_fmamk_f32 v74, v74, 0x3dd53b94, v191
	v_fmamk_f32 v75, v75, 0x3dd53b94, v191
	v_fmamk_f32 v76, v76, 0x3dd53b94, v191
	v_fmamk_f32 v77, v77, 0x3dd53b94, v191
	v_fmamk_f32 v78, v78, 0x3dd53b94, v191
	v_fmamk_f32 v79, v79, 0x3dd53b94, v191
	v_fmamk_f32 v80, v80, 0x3dd53b94, v191
	v_fmac_f32_e32 v191, 0x3dd53b94, v81
	v_exp_f32_e32 v81, v82
	v_exp_f32_e32 v236, v83
	v_exp_f32_e32 v84, v84
	v_exp_f32_e32 v85, v85
	v_exp_f32_e32 v86, v86
	v_exp_f32_e32 v237, v70
	v_add_f32_e32 v70, 0, v81
	v_exp_f32_e32 v87, v87
	v_add_f32_e32 v70, v236, v70
	v_exp_f32_e32 v88, v88
	v_add_f32_e32 v70, v84, v70
	v_exp_f32_e32 v89, v89
	v_add_f32_e32 v70, v85, v70
	v_exp_f32_e32 v90, v90
	v_add_f32_e32 v70, v86, v70
	v_exp_f32_e32 v91, v91
	v_add_f32_e32 v70, v87, v70
	v_exp_f32_e32 v92, v92
	v_add_f32_e32 v70, v88, v70
	v_exp_f32_e32 v93, v93
	v_add_f32_e32 v70, v89, v70
	v_exp_f32_e32 v94, v94
	v_add_f32_e32 v70, v90, v70
	v_exp_f32_e32 v95, v95
	v_add_f32_e32 v70, v91, v70
	v_exp_f32_e32 v96, v96
	v_add_f32_e32 v70, v92, v70
	v_exp_f32_e32 v97, v97
	v_add_f32_e32 v70, v93, v70
	v_exp_f32_e32 v66, v66
	v_add_f32_e32 v70, v94, v70
	v_exp_f32_e32 v67, v67
	v_add_f32_e32 v70, v95, v70
	v_exp_f32_e32 v68, v68
	v_add_f32_e32 v70, v96, v70
	v_exp_f32_e32 v69, v69
	v_add_f32_e32 v70, v97, v70
	v_add_f32_e32 v70, v66, v70
	v_exp_f32_e32 v238, v71
	v_add_f32_e32 v70, v67, v70
	v_exp_f32_e32 v239, v72
	v_add_f32_e32 v70, v68, v70
	v_exp_f32_e32 v73, v73
	v_add_f32_e32 v70, v69, v70
	v_exp_f32_e32 v240, v74
	v_add_f32_e32 v70, v237, v70
	v_exp_f32_e32 v241, v75
	v_add_f32_e32 v70, v238, v70
	v_exp_f32_e32 v242, v76
	v_add_f32_e32 v70, v239, v70
	v_exp_f32_e32 v243, v77
	v_add_f32_e32 v70, v73, v70
	v_exp_f32_e32 v244, v78
	v_add_f32_e32 v70, v240, v70
	v_exp_f32_e32 v245, v79
	v_add_f32_e32 v70, v241, v70
	v_exp_f32_e32 v246, v80
	v_add_f32_e32 v70, v242, v70
	v_mul_f32_e32 v235, 0x3dd53b94, v235
	v_exp_f32_e32 v191, v191
	v_add_f32_e32 v70, v243, v70
	v_exp_f32_e32 v235, v235
	v_add_f32_e32 v70, v244, v70
	v_add_f32_e32 v70, v245, v70
	v_add_f32_e32 v70, v246, v70
	v_add_f32_e32 v82, v191, v70
	v_cndmask_b32_e64 v235, v235, 1.0, vcc
	v_mov_b32_e32 v83, v82
	s_nop 1
	v_permlane32_swap_b32_e32 v82, v83
	v_cmp_gt_f32_e32 vcc, 1.0, v235
	v_cvt_pk_bf16_f32 v78, v81, v236
	v_cvt_pk_bf16_f32 v79, v84, v85
	v_cvt_pk_bf16_f32 v80, v86, v87
	v_cvt_pk_bf16_f32 v81, v88, v89
	v_cvt_pk_bf16_f32 v74, v90, v91
	v_cvt_pk_bf16_f32 v75, v92, v93
	v_cvt_pk_bf16_f32 v76, v94, v95
	v_cvt_pk_bf16_f32 v77, v96, v97
	v_cvt_pk_bf16_f32 v70, v66, v67
	v_cvt_pk_bf16_f32 v71, v68, v69
	v_cvt_pk_bf16_f32 v72, v237, v238
	v_cvt_pk_bf16_f32 v73, v239, v73
	v_cvt_pk_bf16_f32 v66, v240, v241
	v_cvt_pk_bf16_f32 v67, v242, v243
	v_cvt_pk_bf16_f32 v68, v244, v245
	v_cvt_pk_bf16_f32 v69, v246, v191
	s_cbranch_vccz .Lmu_b124
	s_and_saveexec_b64 s[12:13], s[4:5]
	ds_write_b32 v232, v235 offset:128
	s_or_b64 exec, exec, s[12:13]
	s_waitcnt lgkmcnt(0)
	v_add_u32_e32 v96, v196, v202
	ds_read_b128 v[84:87], v96 offset:224
	ds_read_b128 v[88:91], v96 offset:192
	ds_read_b128 v[92:95], v96 offset:160
	ds_read_b128 v[236:239], v96 offset:128
	s_waitcnt lgkmcnt(3)
	v_pk_mul_f32 v[14:15], v[14:15], v[84:85]
	s_waitcnt lgkmcnt(2)
	v_pk_mul_f32 v[10:11], v[10:11], v[88:89]
	s_waitcnt lgkmcnt(1)
	v_pk_mul_f32 v[6:7], v[6:7], v[92:93]
	v_pk_mul_f32 v[16:17], v[16:17], v[86:87]
	v_pk_mul_f32 v[12:13], v[12:13], v[90:91]
	v_pk_mul_f32 v[8:9], v[8:9], v[94:95]
	s_waitcnt lgkmcnt(0)
	v_pk_mul_f32 v[4:5], v[4:5], v[238:239]
	v_pk_mul_f32 v[2:3], v[2:3], v[236:237]
	v_pk_mul_f32 v[30:31], v[30:31], v[84:85]
	v_pk_mul_f32 v[26:27], v[26:27], v[88:89]
	v_pk_mul_f32 v[22:23], v[22:23], v[92:93]
	v_pk_mul_f32 v[32:33], v[32:33], v[86:87]
	v_pk_mul_f32 v[28:29], v[28:29], v[90:91]
	v_pk_mul_f32 v[24:25], v[24:25], v[94:95]
	v_pk_mul_f32 v[20:21], v[20:21], v[238:239]
	v_pk_mul_f32 v[18:19], v[18:19], v[236:237]
	v_pk_mul_f32 v[46:47], v[46:47], v[84:85]
	v_pk_mul_f32 v[42:43], v[42:43], v[88:89]
	v_pk_mul_f32 v[38:39], v[38:39], v[92:93]
	v_pk_mul_f32 v[48:49], v[48:49], v[86:87]
	v_pk_mul_f32 v[44:45], v[44:45], v[90:91]
	v_pk_mul_f32 v[40:41], v[40:41], v[94:95]
	v_pk_mul_f32 v[36:37], v[36:37], v[238:239]
	v_pk_mul_f32 v[34:35], v[34:35], v[236:237]
	v_pk_mul_f32 v[62:63], v[62:63], v[84:85]
	v_pk_mul_f32 v[58:59], v[58:59], v[88:89]
	v_pk_mul_f32 v[54:55], v[54:55], v[92:93]
	v_pk_mul_f32 v[64:65], v[64:65], v[86:87]
	v_pk_mul_f32 v[60:61], v[60:61], v[90:91]
	v_pk_mul_f32 v[56:57], v[56:57], v[94:95]
	v_pk_mul_f32 v[52:53], v[52:53], v[238:239]
	v_pk_mul_f32 v[50:51], v[50:51], v[236:237]
.Lmu_b124:
	v_add_f32_e32 v191, v82, v83
	v_fmac_f32_e32 v191, v234, v235
	ds_read_b64_tr_b16 v[82:83], v233 offset:0
	ds_read_b64_tr_b16 v[84:85], v233 offset:2048
	ds_read_b64_tr_b16 v[86:87], v233 offset:4096
	ds_read_b64_tr_b16 v[88:89], v233 offset:6144
	ds_read_b64_tr_b16 v[90:91], v233 offset:8192
	ds_read_b64_tr_b16 v[92:93], v233 offset:10240
	ds_read_b64_tr_b16 v[94:95], v233 offset:12288
	ds_read_b64_tr_b16 v[96:97], v233 offset:14336
	s_waitcnt lgkmcnt(0)
	s_nop 0
	v_mfma_f32_32x32x16_bf16 v[2:17], v[78:81], v[82:85], v[2:17]
	ds_read_b64_tr_b16 v[82:83], v233 offset:512
	ds_read_b64_tr_b16 v[84:85], v233 offset:2560
	v_mfma_f32_32x32x16_bf16 v[2:17], v[74:77], v[86:89], v[2:17]
	ds_read_b64_tr_b16 v[86:87], v233 offset:4608
	ds_read_b64_tr_b16 v[88:89], v233 offset:6656
	v_mfma_f32_32x32x16_bf16 v[2:17], v[70:73], v[90:93], v[2:17]
	ds_read_b64_tr_b16 v[90:91], v233 offset:8704
	ds_read_b64_tr_b16 v[92:93], v233 offset:10752
	v_mfma_f32_32x32x16_bf16 v[2:17], v[66:69], v[94:97], v[2:17]
	ds_read_b64_tr_b16 v[94:95], v233 offset:12800
	ds_read_b64_tr_b16 v[96:97], v233 offset:14848
	s_waitcnt lgkmcnt(0)
	v_mfma_f32_32x32x16_bf16 v[18:33], v[78:81], v[82:85], v[18:33]
	ds_read_b64_tr_b16 v[82:83], v233 offset:1024
	ds_read_b64_tr_b16 v[84:85], v233 offset:3072
	v_mfma_f32_32x32x16_bf16 v[18:33], v[74:77], v[86:89], v[18:33]
	ds_read_b64_tr_b16 v[86:87], v233 offset:5120
	ds_read_b64_tr_b16 v[88:89], v233 offset:7168
	v_mfma_f32_32x32x16_bf16 v[18:33], v[70:73], v[90:93], v[18:33]
	ds_read_b64_tr_b16 v[90:91], v233 offset:9216
	ds_read_b64_tr_b16 v[92:93], v233 offset:11264
	v_mfma_f32_32x32x16_bf16 v[18:33], v[66:69], v[94:97], v[18:33]
	ds_read_b64_tr_b16 v[94:95], v233 offset:13312
	ds_read_b64_tr_b16 v[96:97], v233 offset:15360
	s_waitcnt lgkmcnt(0)
	v_mfma_f32_32x32x16_bf16 v[34:49], v[78:81], v[82:85], v[34:49]
	ds_read_b64_tr_b16 v[82:83], v233 offset:1536
	ds_read_b64_tr_b16 v[84:85], v233 offset:3584
	v_mfma_f32_32x32x16_bf16 v[34:49], v[74:77], v[86:89], v[34:49]
	ds_read_b64_tr_b16 v[86:87], v233 offset:5632
	ds_read_b64_tr_b16 v[88:89], v233 offset:7680
	v_mfma_f32_32x32x16_bf16 v[34:49], v[70:73], v[90:93], v[34:49]
	ds_read_b64_tr_b16 v[90:91], v233 offset:9728
	ds_read_b64_tr_b16 v[92:93], v233 offset:11776
	v_mfma_f32_32x32x16_bf16 v[34:49], v[66:69], v[94:97], v[34:49]
	ds_read_b64_tr_b16 v[94:95], v233 offset:13824
	ds_read_b64_tr_b16 v[96:97], v233 offset:15872
	s_waitcnt lgkmcnt(0)
	v_mfma_f32_32x32x16_bf16 v[50:65], v[78:81], v[82:85], v[50:65]
	v_mfma_f32_32x32x16_bf16 v[50:65], v[74:77], v[86:89], v[50:65]
	s_add_u32 s10, s10, 0x40000
	s_addc_u32 s11, s11, 0
	s_add_i32 s22, s22, 1
	s_cmp_eq_u32 s21, s10
	v_mfma_f32_32x32x16_bf16 v[50:65], v[70:73], v[90:93], v[50:65]
	s_waitcnt vmcnt(0)
	s_barrier
	v_mfma_f32_32x32x16_bf16 v[50:65], v[66:69], v[94:97], v[50:65]
	s_cbranch_scc1 .LBB0_126
	v_mov_b32_e32 v234, v191
	s_branch .Lmu_a120

.LBB0_285:
	s_lshl_b32 s11, s11, 6
	s_and_b32 s11, s11, 0x100
	s_add_u32 s12, s18, s11
	s_addc_u32 s13, s19, 0
	s_add_u32 s14, s20, s11
	s_addc_u32 s15, s21, 0
	s_ashr_i32 s11, s10, 31
	v_cvt_pk_bf16_f32 v134, v70, v71
	v_cvt_pk_bf16_f32 v135, v72, v73
	v_cvt_pk_bf16_f32 v136, v66, v67
	v_cvt_pk_bf16_f32 v137, v68, v69
	v_cvt_pk_bf16_f32 v142, v62, v63
	v_cvt_pk_bf16_f32 v143, v64, v65
	v_cvt_pk_bf16_f32 v144, v58, v59
	v_cvt_pk_bf16_f32 v145, v60, v61
	v_cvt_pk_bf16_f32 v146, v54, v55
	v_cvt_pk_bf16_f32 v147, v56, v57
	v_cvt_pk_bf16_f32 v148, v50, v51
	v_cvt_pk_bf16_f32 v149, v52, v53
	v_cvt_pk_bf16_f32 v150, v46, v47
	v_cvt_pk_bf16_f32 v151, v48, v49
	v_cvt_pk_bf16_f32 v152, v42, v43
	v_cvt_pk_bf16_f32 v153, v44, v45
	v_cvt_pk_bf16_f32 v154, v38, v39
	v_cvt_pk_bf16_f32 v155, v40, v41
	v_cvt_pk_bf16_f32 v156, v34, v35
	v_cvt_pk_bf16_f32 v157, v32, v33
	v_cvt_pk_bf16_f32 v158, v30, v31
	v_cvt_pk_bf16_f32 v159, v36, v37
	v_cvt_pk_bf16_f32 v160, v78, v81
	v_cvt_pk_bf16_f32 v161, v74, v77
	v_cvt_pk_bf16_f32 v138, v26, v27
	v_cvt_pk_bf16_f32 v139, v28, v29
	v_cvt_pk_bf16_f32 v140, v22, v23
	v_cvt_pk_bf16_f32 v141, v24, v25
	v_cvt_pk_bf16_f32 v130, v18, v19
	v_cvt_pk_bf16_f32 v131, v20, v21
	v_cvt_pk_bf16_f32 v132, v6, v7
	v_cvt_pk_bf16_f32 v133, v2, v3
	v_lshl_add_u64 v[2:3], s[10:11], 0, v[184:185]
	v_mov_b64_e32 v[4:5], s[12:13]
	v_mad_u64_u32 v[6:7], s[24:25], v2, s65, v[4:5]
	v_mad_i32_i24 v7, v3, s65, v7
	v_mov_b32_e32 v195, v1
	v_lshl_add_u64 v[10:11], v[6:7], 0, v[194:195]
	v_lshl_add_u64 v[6:7], v[186:187], 0, s[10:11]
	v_mad_u64_u32 v[4:5], s[24:25], v6, s65, v[4:5]
	v_mad_i32_i24 v5, v7, s65, v5
	v_lshl_add_u64 v[14:15], v[4:5], 0, v[194:195]
	v_mov_b64_e32 v[4:5], s[14:15]
	v_mad_u64_u32 v[8:9], s[24:25], v2, s65, v[4:5]
	v_mad_u64_u32 v[4:5], s[24:25], v6, s65, v[4:5]
	v_mad_i32_i24 v9, v3, s65, v9
	v_mad_i32_i24 v5, v7, s65, v5
	v_lshl_add_u64 v[2:3], v[8:9], 0, v[194:195]
	v_lshl_add_u64 v[6:7], v[4:5], 0, v[194:195]
	global_load_dwordx4 v[2:5], v[2:3], off
	s_nop 0
	global_load_dwordx4 v[6:9], v[6:7], off
	s_nop 0
	global_load_dwordx4 v[10:13], v[10:11], off
	s_nop 0
	global_load_dwordx4 v[14:17], v[14:15], off
	v_lshl_add_u64 v[198:199], s[12:13], 0, v[194:195]
	s_or_b32 s12, s10, 64
	s_ashr_i32 s13, s12, 31
	v_add_u32_e32 v62, 16, v222
	v_lshl_add_u64 v[200:201], s[14:15], 0, v[194:195]
	v_lshl_add_u64 v[18:19], s[12:13], 0, v[184:185]
	v_add_u32_e32 v63, 16, v223
	v_add_u32_e32 v64, 16, v224
	v_add_u32_e32 v67, 16, v225
	v_lshl_add_u64 v[20:21], v[186:187], 0, s[12:13]
	v_mad_u64_u32 v[22:23], s[12:13], v18, s65, v[198:199]
	s_waitcnt vmcnt(0)
	v_mad_u64_u32 v[24:25], s[12:13], v20, s65, v[198:199]
	v_mad_i32_i24 v23, v19, s65, v23
	v_mad_i32_i24 v25, v21, s65, v25
	s_waitcnt vmcnt(3)
	ds_write_b128 v62, v[2:5]
	s_waitcnt vmcnt(2)
	ds_write_b128 v63, v[6:9]
	s_waitcnt vmcnt(1)
	ds_write_b128 v64, v[10:13] offset:32768
	s_waitcnt vmcnt(0)
	ds_write_b128 v67, v[14:17] offset:32768
	v_mad_u64_u32 v[2:3], s[12:13], v18, s65, v[200:201]
	v_mad_i32_i24 v3, v19, s65, v3
	v_mad_u64_u32 v[4:5], s[12:13], v20, s65, v[200:201]
	s_waitcnt lgkmcnt(0)
	s_barrier
	global_load_dwordx4 v[50:53], v[22:23], off
	global_load_dwordx4 v[68:71], v[24:25], off
	v_mad_i32_i24 v5, v21, s65, v5
	global_load_dwordx4 v[54:57], v[2:3], off
	global_load_dwordx4 v[58:61], v[4:5], off
	v_add_u32_e32 v6, v227, v228
	ds_read_b128 v[2:5], v6 offset:32768
	ds_read_b128 v[18:21], v6 offset:40960
	v_add_u32_e32 v38, v227, v229
	ds_read_b128 v[34:37], v38 offset:32768
	ds_read_b128 v[38:41], v38 offset:40960
	s_waitcnt lgkmcnt(3)
	v_mfma_f32_32x32x16_bf16 v[2:17], v[2:5], v[134:137], 0
	s_waitcnt lgkmcnt(2)
	v_mfma_f32_32x32x16_bf16 v[18:33], v[18:21], v[134:137], 0
	s_waitcnt lgkmcnt(1)
	v_mfma_f32_32x32x16_bf16 v[2:17], v[34:37], v[142:145], v[2:17]
	s_waitcnt lgkmcnt(0)
	v_mfma_f32_32x32x16_bf16 v[18:33], v[38:41], v[142:145], v[18:33]
	v_add_u32_e32 v38, v227, v230
	ds_read_b128 v[34:37], v38 offset:32768
	ds_read_b128 v[38:41], v38 offset:40960
	s_waitcnt lgkmcnt(1)
	v_mfma_f32_32x32x16_bf16 v[2:17], v[34:37], v[146:149], v[2:17]
	s_waitcnt lgkmcnt(0)
	v_mfma_f32_32x32x16_bf16 v[18:33], v[38:41], v[146:149], v[18:33]
	v_add_u32_e32 v38, v227, v231
	ds_read_b128 v[34:37], v38 offset:32768
	ds_read_b128 v[38:41], v38 offset:40960
	s_waitcnt lgkmcnt(1)
	v_mfma_f32_32x32x16_bf16 v[2:17], v[34:37], v[150:153], v[2:17]
	s_waitcnt lgkmcnt(0)
	v_mfma_f32_32x32x16_bf16 v[18:33], v[38:41], v[150:153], v[18:33]
	v_add_u32_e32 v38, v227, v232
	ds_read_b128 v[34:37], v38 offset:32768
	ds_read_b128 v[38:41], v38 offset:40960
	s_waitcnt lgkmcnt(1)
	v_mfma_f32_32x32x16_bf16 v[2:17], v[34:37], v[154:157], v[2:17]
	s_waitcnt lgkmcnt(0)
	v_mfma_f32_32x32x16_bf16 v[18:33], v[38:41], v[154:157], v[18:33]
	v_add_u32_e32 v38, v227, v233
	ds_read_b128 v[34:37], v38 offset:32768
	ds_read_b128 v[38:41], v38 offset:40960
	s_waitcnt lgkmcnt(1)
	v_mfma_f32_32x32x16_bf16 v[2:17], v[34:37], v[158:161], v[2:17]
	s_waitcnt lgkmcnt(0)
	v_mfma_f32_32x32x16_bf16 v[18:33], v[38:41], v[158:161], v[18:33]
	v_add_u32_e32 v38, v227, v234
	ds_read_b128 v[34:37], v38 offset:32768
	ds_read_b128 v[38:41], v38 offset:40960
	s_waitcnt lgkmcnt(1)
	v_mfma_f32_32x32x16_bf16 v[2:17], v[34:37], v[138:141], v[2:17]
	s_waitcnt lgkmcnt(0)
	v_mfma_f32_32x32x16_bf16 v[18:33], v[38:41], v[138:141], v[18:33]
	v_add_u32_e32 v38, v227, v235
	ds_read_b128 v[34:37], v38 offset:32768
	ds_read_b128 v[38:41], v38 offset:40960
	s_waitcnt lgkmcnt(1)
	v_mfma_f32_32x32x16_bf16 v[2:17], v[34:37], v[130:133], v[2:17]
	s_waitcnt lgkmcnt(0)
	v_mfma_f32_32x32x16_bf16 v[18:33], v[38:41], v[130:133], v[18:33]
	s_nop 9
	v_max_f32_e32 v34, v3, v3
	v_max_f32_e32 v35, v2, v2
	v_max_f32_e32 v34, v35, v34
	v_max3_f32 v34, v34, v4, v5
	v_max3_f32 v34, v34, v6, v7
	v_max3_f32 v34, v34, v8, v9
	v_max3_f32 v34, v34, v10, v11
	v_max3_f32 v34, v34, v12, v13
	v_max3_f32 v34, v34, v14, v15
	v_max3_f32 v34, v34, v16, v17
	v_max3_f32 v34, v34, v18, v19
	v_max3_f32 v34, v34, v20, v21
	v_max3_f32 v34, v34, v22, v23
	v_max3_f32 v34, v34, v24, v25
	v_max3_f32 v34, v34, v26, v27
	v_max3_f32 v34, v34, v28, v29
	v_max3_f32 v34, v34, v30, v31
	v_max3_f32 v34, v34, v32, v33
	v_mov_b32_e32 v35, v34
	s_nop 1
	v_permlane32_swap_b32_e32 v34, v35
	v_max_f32_e32 v35, v35, v35
	v_max_f32_e32 v34, v34, v34
	v_max_f32_e32 v35, v34, v35
	v_sub_f32_e32 v2, v2, v35
	v_sub_f32_e32 v3, v3, v35
	v_exp_f32_e32 v2, v2
	v_sub_f32_e32 v4, v4, v35
	v_exp_f32_e32 v3, v3
	v_sub_f32_e32 v5, v5, v35
	v_exp_f32_e32 v4, v4
	v_sub_f32_e32 v6, v6, v35
	v_exp_f32_e32 v5, v5
	v_sub_f32_e32 v7, v7, v35
	v_exp_f32_e32 v6, v6
	v_add_f32_e32 v34, 0, v2
	v_sub_f32_e32 v8, v8, v35
	v_exp_f32_e32 v7, v7
	v_add_f32_e32 v34, v3, v34
	v_sub_f32_e32 v9, v9, v35
	v_exp_f32_e32 v8, v8
	v_add_f32_e32 v34, v4, v34
	v_sub_f32_e32 v10, v10, v35
	v_exp_f32_e32 v9, v9
	v_add_f32_e32 v34, v5, v34
	v_sub_f32_e32 v11, v11, v35
	v_exp_f32_e32 v10, v10
	v_add_f32_e32 v34, v6, v34
	v_sub_f32_e32 v12, v12, v35
	v_exp_f32_e32 v11, v11
	v_add_f32_e32 v34, v7, v34
	v_sub_f32_e32 v13, v13, v35
	v_exp_f32_e32 v12, v12
	v_add_f32_e32 v34, v8, v34
	v_sub_f32_e32 v14, v14, v35
	v_exp_f32_e32 v13, v13
	v_add_f32_e32 v34, v9, v34
	v_sub_f32_e32 v15, v15, v35
	v_exp_f32_e32 v14, v14
	v_add_f32_e32 v34, v10, v34
	v_sub_f32_e32 v16, v16, v35
	v_exp_f32_e32 v15, v15
	v_add_f32_e32 v34, v11, v34
	v_sub_f32_e32 v17, v17, v35
	v_exp_f32_e32 v16, v16
	v_add_f32_e32 v34, v12, v34
	v_sub_f32_e32 v18, v18, v35
	v_exp_f32_e32 v17, v17
	v_add_f32_e32 v34, v13, v34
	v_sub_f32_e32 v19, v19, v35
	v_exp_f32_e32 v18, v18
	v_add_f32_e32 v34, v14, v34
	v_sub_f32_e32 v20, v20, v35
	v_exp_f32_e32 v19, v19
	v_add_f32_e32 v34, v15, v34
	v_sub_f32_e32 v21, v21, v35
	v_exp_f32_e32 v20, v20
	v_add_f32_e32 v34, v16, v34
	v_sub_f32_e32 v22, v22, v35
	v_exp_f32_e32 v21, v21
	v_add_f32_e32 v34, v17, v34
	v_sub_f32_e32 v23, v23, v35
	v_exp_f32_e32 v22, v22
	v_add_f32_e32 v34, v18, v34
	v_sub_f32_e32 v24, v24, v35
	v_exp_f32_e32 v23, v23
	v_add_f32_e32 v34, v19, v34
	v_sub_f32_e32 v25, v25, v35
	v_exp_f32_e32 v24, v24
	v_add_f32_e32 v34, v20, v34
	v_sub_f32_e32 v26, v26, v35
	v_exp_f32_e32 v25, v25
	v_add_f32_e32 v34, v21, v34
	v_sub_f32_e32 v27, v27, v35
	v_exp_f32_e32 v26, v26
	v_add_f32_e32 v34, v22, v34
	v_sub_f32_e32 v28, v28, v35
	v_exp_f32_e32 v27, v27
	v_add_f32_e32 v34, v23, v34
	v_sub_f32_e32 v29, v29, v35
	v_exp_f32_e32 v28, v28
	v_add_f32_e32 v34, v24, v34
	v_sub_f32_e32 v30, v30, v35
	v_exp_f32_e32 v29, v29
	v_add_f32_e32 v34, v25, v34
	v_sub_f32_e32 v31, v31, v35
	v_exp_f32_e32 v30, v30
	v_add_f32_e32 v34, v26, v34
	v_sub_f32_e32 v32, v32, v35
	v_exp_f32_e32 v31, v31
	v_add_f32_e32 v34, v27, v34
	v_sub_f32_e32 v33, v33, v35
	v_exp_f32_e32 v32, v32
	v_add_f32_e32 v34, v28, v34
	v_exp_f32_e32 v33, v33
	v_add_f32_e32 v34, v29, v34
	v_add_f32_e32 v34, v30, v34
	v_add_f32_e32 v34, v31, v34
	v_add_f32_e32 v34, v32, v34
	v_add_f32_e32 v34, v33, v34
	v_mov_b32_e32 v36, v34
	s_nop 1
	v_permlane32_swap_b32_e32 v34, v36
	v_add_f32_e32 v34, v34, v36
	v_pk_add_f32 v[202:203], v[34:35], 0 op_sel_hi:[1,0]
	v_cvt_pk_bf16_f32 v72, v2, v3
	v_cvt_pk_bf16_f32 v73, v4, v5
	v_cvt_pk_bf16_f32 v74, v6, v7
	v_cvt_pk_bf16_f32 v75, v8, v9
	v_cvt_pk_bf16_f32 v76, v10, v11
	s_nop 0
	v_xor_b32_e32 v66, 0x80000000, v203
	v_cvt_pk_bf16_f32 v77, v12, v13
	v_cvt_pk_bf16_f32 v78, v14, v15
	v_cvt_pk_bf16_f32 v79, v16, v17
	v_cvt_pk_bf16_f32 v80, v18, v19
	v_cvt_pk_bf16_f32 v81, v20, v21
	v_cvt_pk_bf16_f32 v82, v22, v23
	v_cvt_pk_bf16_f32 v83, v24, v25
	v_cvt_pk_bf16_f32 v84, v26, v27
	v_cvt_pk_bf16_f32 v85, v28, v29
	v_cvt_pk_bf16_f32 v86, v30, v31
	v_cvt_pk_bf16_f32 v87, v32, v33
	ds_read_b64_tr_b16 v[2:3], v237 offset:0
	ds_read_b64_tr_b16 v[4:5], v237 offset:0x800
	ds_read_b64_tr_b16 v[18:19], v237 offset:0x1000
	ds_read_b64_tr_b16 v[20:21], v237 offset:0x1800
	ds_read_b64_tr_b16 v[22:23], v237 offset:0x2000
	ds_read_b64_tr_b16 v[24:25], v237 offset:0x2800
	ds_read_b64_tr_b16 v[26:27], v237 offset:0x3000
	ds_read_b64_tr_b16 v[28:29], v237 offset:0x3800
	s_waitcnt lgkmcnt(0)
	s_nop 0
	v_mfma_f32_32x32x16_bf16 v[2:17], v[72:75], v[2:5], 0
	v_mfma_f32_32x32x16_bf16 v[2:17], v[76:79], v[18:21], v[2:17]
	ds_read_b64_tr_b16 v[18:19], v237 offset:0x200
	ds_read_b64_tr_b16 v[20:21], v237 offset:0xa00
	ds_read_b64_tr_b16 v[34:35], v237 offset:0x1200
	ds_read_b64_tr_b16 v[36:37], v237 offset:0x1a00
	ds_read_b64_tr_b16 v[38:39], v237 offset:0x2200
	ds_read_b64_tr_b16 v[40:41], v237 offset:0x2a00
	ds_read_b64_tr_b16 v[42:43], v237 offset:0x3200
	v_mfma_f32_32x32x16_bf16 v[2:17], v[80:83], v[22:25], v[2:17]
	ds_read_b64_tr_b16 v[44:45], v237 offset:0x3a00
	s_waitcnt lgkmcnt(0)
	v_mfma_f32_32x32x16_bf16 v[2:17], v[84:87], v[26:29], v[2:17]
	v_mfma_f32_32x32x16_bf16 v[18:33], v[72:75], v[18:21], 0
	v_mfma_f32_32x32x16_bf16 v[18:33], v[76:79], v[34:37], v[18:33]
	ds_read_b64_tr_b16 v[34:35], v237 offset:0x400
	ds_read_b64_tr_b16 v[36:37], v237 offset:0xc00
	ds_read_b64_tr_b16 v[88:89], v237 offset:0x1400
	ds_read_b64_tr_b16 v[90:91], v237 offset:0x1c00
	ds_read_b64_tr_b16 v[92:93], v237 offset:0x2400
	ds_read_b64_tr_b16 v[94:95], v237 offset:0x2c00
	ds_read_b64_tr_b16 v[96:97], v237 offset:0x3400
	v_mfma_f32_32x32x16_bf16 v[18:33], v[80:83], v[38:41], v[18:33]
	ds_read_b64_tr_b16 v[98:99], v237 offset:0x3c00
	s_waitcnt lgkmcnt(0)
	v_mfma_f32_32x32x16_bf16 v[18:33], v[84:87], v[42:45], v[18:33]
	v_mfma_f32_32x32x16_bf16 v[34:49], v[72:75], v[34:37], 0
	v_mfma_f32_32x32x16_bf16 v[34:49], v[76:79], v[88:91], v[34:49]
	ds_read_b64_tr_b16 v[88:89], v237 offset:0x600
	ds_read_b64_tr_b16 v[90:91], v237 offset:0xe00
	v_mfma_f32_32x32x16_bf16 v[34:49], v[80:83], v[92:95], v[34:49]
	ds_read_b64_tr_b16 v[92:93], v237 offset:0x1600
	ds_read_b64_tr_b16 v[94:95], v237 offset:0x1e00
	v_mfma_f32_32x32x16_bf16 v[34:49], v[84:87], v[96:99], v[34:49]
	ds_read_b64_tr_b16 v[96:97], v237 offset:0x2600
	ds_read_b64_tr_b16 v[98:99], v237 offset:0x2e00
	ds_read_b64_tr_b16 v[100:101], v237 offset:0x3600
	ds_read_b64_tr_b16 v[102:103], v237 offset:0x3e00
	s_waitcnt lgkmcnt(0)
	s_waitcnt vmcnt(1)
	ds_write_b128 v62, v[54:57] offset:16384
	s_waitcnt vmcnt(0)
	ds_write_b128 v63, v[58:61] offset:16384
	ds_write_b128 v64, v[50:53] offset:49152
	v_mfma_f32_32x32x16_bf16 v[50:65], v[72:75], v[88:91], 0
	ds_write_b128 v67, v[68:71] offset:49152
	s_addk_i32 s10, 0x80
	s_mov_b32 s14, 0
	s_movk_i32 s15, 0x4000
	v_mov_b32_e32 v67, v66
	v_mov_b32_e32 v68, v66
	v_mov_b32_e32 v69, v66
	v_mfma_f32_32x32x16_bf16 v[50:65], v[76:79], v[92:95], v[50:65]
	v_mov_b32_e32 v70, v66
	v_mov_b32_e32 v71, v66
	v_mov_b32_e32 v72, v66
	v_mov_b32_e32 v73, v66
	v_mov_b32_e32 v74, v66
	v_mov_b32_e32 v75, v66
	v_mov_b32_e32 v76, v66
	v_mfma_f32_32x32x16_bf16 v[50:65], v[80:83], v[96:99], v[50:65]
	v_mov_b32_e32 v77, v66
	v_mov_b32_e32 v78, v66
	v_mov_b32_e32 v79, v66
	v_mov_b32_e32 v80, v66
	v_mov_b32_e32 v81, v66
	s_waitcnt lgkmcnt(0)
	s_barrier
	v_mfma_f32_32x32x16_bf16 v[50:65], v[84:87], v[100:103], v[50:65]
	s_and_b32 s24, s22, 7
	s_lshl_b32 s24, s24, 6
	s_and_b32 s24, s24, 0x100
	s_mul_i32 s25, s10, 0x1400
	s_add_u32 s24, s24, s25
	s_add_u32 s24, s18, s24
	s_addc_u32 s25, s19, 0
	v_readlane_b32 s26, v254, 10
	s_nop 3
	s_lshl_b32 s26, s26, 5
	s_add_i32 s26, s26, 16
	v_add_u32_e32 v162, v227, v228
	v_add_u32_e32 v163, v227, v229
	v_add_u32_e32 v164, v227, v230
	v_add_u32_e32 v165, v227, v231
	v_add_u32_e32 v166, v227, v232
	v_add_u32_e32 v167, v227, v233
	v_add_u32_e32 v168, v227, v234
	v_add_u32_e32 v169, v227, v235
.Lgu_a286:
	ds_read_b128 v[82:85], v162 offset:49152
	ds_read_b128 v[86:89], v162 offset:57344
	s_waitcnt lgkmcnt(1)
	v_mfma_f32_32x32x16_bf16 v[114:129], v[82:85], v[134:137], v[66:81]
	s_waitcnt lgkmcnt(0)
	v_mfma_f32_32x32x16_bf16 v[98:113], v[86:89], v[134:137], v[66:81]
	ds_read_b128 v[82:85], v163 offset:49152
	ds_read_b128 v[86:89], v163 offset:57344
	s_waitcnt lgkmcnt(1)
	v_mfma_f32_32x32x16_bf16 v[114:129], v[82:85], v[142:145], v[114:129]
	s_waitcnt lgkmcnt(0)
	v_mfma_f32_32x32x16_bf16 v[98:113], v[86:89], v[142:145], v[98:113]
	ds_read_b128 v[82:85], v164 offset:49152
	ds_read_b128 v[86:89], v164 offset:57344
	s_waitcnt lgkmcnt(1)
	v_mfma_f32_32x32x16_bf16 v[114:129], v[82:85], v[146:149], v[114:129]
	s_waitcnt lgkmcnt(0)
	v_mfma_f32_32x32x16_bf16 v[98:113], v[86:89], v[146:149], v[98:113]
	ds_read_b128 v[82:85], v165 offset:49152
	ds_read_b128 v[86:89], v165 offset:57344
	s_waitcnt lgkmcnt(1)
	v_mfma_f32_32x32x16_bf16 v[114:129], v[82:85], v[150:153], v[114:129]
	s_waitcnt lgkmcnt(0)
	v_mfma_f32_32x32x16_bf16 v[98:113], v[86:89], v[150:153], v[98:113]
	ds_read_b128 v[82:85], v166 offset:49152
	ds_read_b128 v[86:89], v166 offset:57344
	s_waitcnt lgkmcnt(1)
	v_mfma_f32_32x32x16_bf16 v[114:129], v[82:85], v[154:157], v[114:129]
	s_waitcnt lgkmcnt(0)
	v_mfma_f32_32x32x16_bf16 v[98:113], v[86:89], v[154:157], v[98:113]
	ds_read_b128 v[82:85], v167 offset:49152
	ds_read_b128 v[86:89], v167 offset:57344
	s_waitcnt lgkmcnt(1)
	v_mfma_f32_32x32x16_bf16 v[114:129], v[82:85], v[158:161], v[114:129]
	s_waitcnt lgkmcnt(0)
	v_mfma_f32_32x32x16_bf16 v[98:113], v[86:89], v[158:161], v[98:113]
	ds_read_b128 v[82:85], v168 offset:49152
	ds_read_b128 v[86:89], v168 offset:57344
	s_waitcnt lgkmcnt(1)
	v_mfma_f32_32x32x16_bf16 v[114:129], v[82:85], v[138:141], v[114:129]
	s_waitcnt lgkmcnt(0)
	v_mfma_f32_32x32x16_bf16 v[98:113], v[86:89], v[138:141], v[98:113]
	ds_read_b128 v[82:85], v169 offset:49152
	ds_read_b128 v[86:89], v169 offset:57344
	s_waitcnt lgkmcnt(1)
	v_mfma_f32_32x32x16_bf16 v[114:129], v[82:85], v[130:133], v[114:129]
	s_waitcnt lgkmcnt(0)
	v_mfma_f32_32x32x16_bf16 v[98:113], v[86:89], v[130:133], v[98:113]
	s_mov_b32 m0, s26
	s_nop 0
	global_load_lds_dwordx4 v250, s[24:25]
	s_add_i32 m0, s26, 0x400
	s_nop 0
	global_load_lds_dwordx4 v251, s[24:25]
	s_add_i32 m0, s26, 0x8000
	s_nop 0
	global_load_lds_dwordx4 v252, s[24:25]
	s_add_i32 m0, s26, 0x8400
	s_nop 0
	global_load_lds_dwordx4 v253, s[24:25]
	s_add_u32 s24, s24, 0x50000
	s_addc_u32 s25, s25, 0
	s_nop 1
	v_max_f32_e32 v82, v115, v115
	v_max_f32_e32 v83, v114, v114
	v_max_f32_e32 v82, v83, v82
	v_max3_f32 v82, v82, v116, v117
	v_max3_f32 v82, v82, v118, v119
	v_max3_f32 v82, v82, v120, v121
	v_max3_f32 v82, v82, v122, v123
	v_max3_f32 v82, v82, v124, v125
	v_max3_f32 v82, v82, v126, v127
	v_max3_f32 v82, v82, v128, v129
	v_max3_f32 v82, v82, v98, v99
	v_max3_f32 v82, v82, v100, v101
	v_max3_f32 v82, v82, v102, v103
	v_max3_f32 v82, v82, v104, v105
	v_max3_f32 v82, v82, v106, v107
	v_max3_f32 v82, v82, v108, v109
	v_max3_f32 v82, v82, v110, v111
	v_max3_f32 v82, v82, v112, v113
	v_mov_b32_e32 v83, v82
	s_nop 1
	v_permlane32_swap_b32_e32 v82, v83
	v_max_f32_e32 v83, v83, v83
	v_max_f32_e32 v82, v82, v82
	v_max_f32_e32 v82, v82, v83
	v_cmp_ge_f32_e32 vcc, s64, v82
	s_cmp_eq_u64 vcc, exec
	s_cbranch_scc0 .Lgu_a294
	v_mov_b32_e32 v195, 1.0

.Lgu_a292:
	v_add_f32_e32 v114, v114, v115
	v_fmac_f32_e32 v114, v202, v195
	ds_read_b64_tr_b16 v[116:117], v237 offset:16384
	ds_read_b64_tr_b16 v[118:119], v237 offset:18432
	ds_read_b64_tr_b16 v[120:121], v237 offset:20480
	ds_read_b64_tr_b16 v[122:123], v237 offset:22528
	ds_read_b64_tr_b16 v[124:125], v237 offset:24576
	ds_read_b64_tr_b16 v[126:127], v237 offset:26624
	ds_read_b64_tr_b16 v[238:239], v237 offset:28672
	ds_read_b64_tr_b16 v[240:241], v237 offset:30720
	s_waitcnt lgkmcnt(0)
	s_nop 0
	v_mfma_f32_32x32x16_bf16 v[2:17], v[110:113], v[116:119], v[2:17]
	ds_read_b64_tr_b16 v[116:117], v237 offset:16896
	ds_read_b64_tr_b16 v[118:119], v237 offset:18944
	v_mfma_f32_32x32x16_bf16 v[2:17], v[106:109], v[120:123], v[2:17]
	ds_read_b64_tr_b16 v[120:121], v237 offset:20992
	ds_read_b64_tr_b16 v[122:123], v237 offset:23040
	v_mfma_f32_32x32x16_bf16 v[2:17], v[102:105], v[124:127], v[2:17]
	ds_read_b64_tr_b16 v[124:125], v237 offset:25088
	ds_read_b64_tr_b16 v[126:127], v237 offset:27136
	v_mfma_f32_32x32x16_bf16 v[2:17], v[98:101], v[238:241], v[2:17]
	ds_read_b64_tr_b16 v[238:239], v237 offset:29184
	ds_read_b64_tr_b16 v[240:241], v237 offset:31232
	s_waitcnt lgkmcnt(0)
	v_mfma_f32_32x32x16_bf16 v[18:33], v[110:113], v[116:119], v[18:33]
	ds_read_b64_tr_b16 v[116:117], v237 offset:17408
	ds_read_b64_tr_b16 v[118:119], v237 offset:19456
	v_mfma_f32_32x32x16_bf16 v[18:33], v[106:109], v[120:123], v[18:33]
	ds_read_b64_tr_b16 v[120:121], v237 offset:21504
	ds_read_b64_tr_b16 v[122:123], v237 offset:23552
	v_mfma_f32_32x32x16_bf16 v[18:33], v[102:105], v[124:127], v[18:33]
	ds_read_b64_tr_b16 v[124:125], v237 offset:25600
	ds_read_b64_tr_b16 v[126:127], v237 offset:27648
	v_mfma_f32_32x32x16_bf16 v[18:33], v[98:101], v[238:241], v[18:33]
	ds_read_b64_tr_b16 v[238:239], v237 offset:29696
	ds_read_b64_tr_b16 v[240:241], v237 offset:31744
	s_waitcnt lgkmcnt(0)
	v_mfma_f32_32x32x16_bf16 v[34:49], v[110:113], v[116:119], v[34:49]
	ds_read_b64_tr_b16 v[116:117], v237 offset:17920
	ds_read_b64_tr_b16 v[118:119], v237 offset:19968
	v_mfma_f32_32x32x16_bf16 v[34:49], v[106:109], v[120:123], v[34:49]
	ds_read_b64_tr_b16 v[120:121], v237 offset:22016
	ds_read_b64_tr_b16 v[122:123], v237 offset:24064
	v_mfma_f32_32x32x16_bf16 v[34:49], v[102:105], v[124:127], v[34:49]
	ds_read_b64_tr_b16 v[124:125], v237 offset:26112
	ds_read_b64_tr_b16 v[126:127], v237 offset:28160
	v_mfma_f32_32x32x16_bf16 v[34:49], v[98:101], v[238:241], v[34:49]
	ds_read_b64_tr_b16 v[238:239], v237 offset:30208
	ds_read_b64_tr_b16 v[240:241], v237 offset:32256
	s_waitcnt lgkmcnt(0)
	v_mfma_f32_32x32x16_bf16 v[50:65], v[110:113], v[116:119], v[50:65]
	s_add_i32 s14, s14, 1
	s_cmp_eq_u32 s23, s14
	v_mfma_f32_32x32x16_bf16 v[50:65], v[106:109], v[120:123], v[50:65]
	s_waitcnt vmcnt(0)
	v_mfma_f32_32x32x16_bf16 v[50:65], v[102:105], v[124:127], v[50:65]
	s_barrier
	v_mfma_f32_32x32x16_bf16 v[50:65], v[98:101], v[238:241], v[50:65]
	v_mov_b32_e32 v202, v114
.Lgu_b286:
	ds_read_b128 v[82:85], v162 offset:32768
	ds_read_b128 v[86:89], v162 offset:40960
	s_waitcnt lgkmcnt(1)
	v_mfma_f32_32x32x16_bf16 v[114:129], v[82:85], v[134:137], v[66:81]
	s_waitcnt lgkmcnt(0)
	v_mfma_f32_32x32x16_bf16 v[98:113], v[86:89], v[134:137], v[66:81]
	ds_read_b128 v[82:85], v163 offset:32768
	ds_read_b128 v[86:89], v163 offset:40960
	s_waitcnt lgkmcnt(1)
	v_mfma_f32_32x32x16_bf16 v[114:129], v[82:85], v[142:145], v[114:129]
	s_waitcnt lgkmcnt(0)
	v_mfma_f32_32x32x16_bf16 v[98:113], v[86:89], v[142:145], v[98:113]
	ds_read_b128 v[82:85], v164 offset:32768
	ds_read_b128 v[86:89], v164 offset:40960
	s_waitcnt lgkmcnt(1)
	v_mfma_f32_32x32x16_bf16 v[114:129], v[82:85], v[146:149], v[114:129]
	s_waitcnt lgkmcnt(0)
	v_mfma_f32_32x32x16_bf16 v[98:113], v[86:89], v[146:149], v[98:113]
	ds_read_b128 v[82:85], v165 offset:32768
	ds_read_b128 v[86:89], v165 offset:40960
	s_waitcnt lgkmcnt(1)
	v_mfma_f32_32x32x16_bf16 v[114:129], v[82:85], v[150:153], v[114:129]
	s_waitcnt lgkmcnt(0)
	v_mfma_f32_32x32x16_bf16 v[98:113], v[86:89], v[150:153], v[98:113]
	ds_read_b128 v[82:85], v166 offset:32768
	ds_read_b128 v[86:89], v166 offset:40960
	s_waitcnt lgkmcnt(1)
	v_mfma_f32_32x32x16_bf16 v[114:129], v[82:85], v[154:157], v[114:129]
	s_waitcnt lgkmcnt(0)
	v_mfma_f32_32x32x16_bf16 v[98:113], v[86:89], v[154:157], v[98:113]
	ds_read_b128 v[82:85], v167 offset:32768
	ds_read_b128 v[86:89], v167 offset:40960
	s_waitcnt lgkmcnt(1)
	v_mfma_f32_32x32x16_bf16 v[114:129], v[82:85], v[158:161], v[114:129]
	s_waitcnt lgkmcnt(0)
	v_mfma_f32_32x32x16_bf16 v[98:113], v[86:89], v[158:161], v[98:113]
	ds_read_b128 v[82:85], v168 offset:32768
	ds_read_b128 v[86:89], v168 offset:40960
	s_waitcnt lgkmcnt(1)
	v_mfma_f32_32x32x16_bf16 v[114:129], v[82:85], v[138:141], v[114:129]
	s_waitcnt lgkmcnt(0)
	v_mfma_f32_32x32x16_bf16 v[98:113], v[86:89], v[138:141], v[98:113]
	ds_read_b128 v[82:85], v169 offset:32768
	ds_read_b128 v[86:89], v169 offset:40960
	s_waitcnt lgkmcnt(1)
	v_mfma_f32_32x32x16_bf16 v[114:129], v[82:85], v[130:133], v[114:129]
	s_waitcnt lgkmcnt(0)
	v_mfma_f32_32x32x16_bf16 v[98:113], v[86:89], v[130:133], v[98:113]
	s_add_i32 m0, s26, 0x4000
	s_nop 0
	global_load_lds_dwordx4 v250, s[24:25]
	s_add_i32 m0, s26, 0x4400
	s_nop 0
	global_load_lds_dwordx4 v251, s[24:25]
	s_add_i32 m0, s26, 0xc000
	s_nop 0
	global_load_lds_dwordx4 v252, s[24:25]
	s_add_i32 m0, s26, 0xc400
	s_nop 0
	global_load_lds_dwordx4 v253, s[24:25]
	s_add_u32 s24, s24, 0x50000
	s_addc_u32 s25, s25, 0
	s_nop 1
	v_max_f32_e32 v82, v115, v115
	v_max_f32_e32 v83, v114, v114
	v_max_f32_e32 v82, v83, v82
	v_max3_f32 v82, v82, v116, v117
	v_max3_f32 v82, v82, v118, v119
	v_max3_f32 v82, v82, v120, v121
	v_max3_f32 v82, v82, v122, v123
	v_max3_f32 v82, v82, v124, v125
	v_max3_f32 v82, v82, v126, v127
	v_max3_f32 v82, v82, v128, v129
	v_max3_f32 v82, v82, v98, v99
	v_max3_f32 v82, v82, v100, v101
	v_max3_f32 v82, v82, v102, v103
	v_max3_f32 v82, v82, v104, v105
	v_max3_f32 v82, v82, v106, v107
	v_max3_f32 v82, v82, v108, v109
	v_max3_f32 v82, v82, v110, v111
	v_max3_f32 v82, v82, v112, v113
	v_mov_b32_e32 v83, v82
	s_nop 1
	v_permlane32_swap_b32_e32 v82, v83
	v_max_f32_e32 v83, v83, v83
	v_max_f32_e32 v82, v82, v82
	v_max_f32_e32 v82, v82, v83
	v_cmp_ge_f32_e32 vcc, s64, v82
	s_cmp_eq_u64 vcc, exec
	s_cbranch_scc0 .Lgu_b294
	v_mov_b32_e32 v195, 1.0

.Lgu_b292:
	v_add_f32_e32 v114, v114, v115
	v_fmac_f32_e32 v114, v202, v195
	ds_read_b64_tr_b16 v[116:117], v237 offset:0
	ds_read_b64_tr_b16 v[118:119], v237 offset:2048
	ds_read_b64_tr_b16 v[120:121], v237 offset:4096
	ds_read_b64_tr_b16 v[122:123], v237 offset:6144
	ds_read_b64_tr_b16 v[124:125], v237 offset:8192
	ds_read_b64_tr_b16 v[126:127], v237 offset:10240
	ds_read_b64_tr_b16 v[238:239], v237 offset:12288
	ds_read_b64_tr_b16 v[240:241], v237 offset:14336
	s_waitcnt lgkmcnt(0)
	s_nop 0
	v_mfma_f32_32x32x16_bf16 v[2:17], v[110:113], v[116:119], v[2:17]
	ds_read_b64_tr_b16 v[116:117], v237 offset:512
	ds_read_b64_tr_b16 v[118:119], v237 offset:2560
	v_mfma_f32_32x32x16_bf16 v[2:17], v[106:109], v[120:123], v[2:17]
	ds_read_b64_tr_b16 v[120:121], v237 offset:4608
	ds_read_b64_tr_b16 v[122:123], v237 offset:6656
	v_mfma_f32_32x32x16_bf16 v[2:17], v[102:105], v[124:127], v[2:17]
	ds_read_b64_tr_b16 v[124:125], v237 offset:8704
	ds_read_b64_tr_b16 v[126:127], v237 offset:10752
	v_mfma_f32_32x32x16_bf16 v[2:17], v[98:101], v[238:241], v[2:17]
	ds_read_b64_tr_b16 v[238:239], v237 offset:12800
	ds_read_b64_tr_b16 v[240:241], v237 offset:14848
	s_waitcnt lgkmcnt(0)
	v_mfma_f32_32x32x16_bf16 v[18:33], v[110:113], v[116:119], v[18:33]
	ds_read_b64_tr_b16 v[116:117], v237 offset:1024
	ds_read_b64_tr_b16 v[118:119], v237 offset:3072
	v_mfma_f32_32x32x16_bf16 v[18:33], v[106:109], v[120:123], v[18:33]
	ds_read_b64_tr_b16 v[120:121], v237 offset:5120
	ds_read_b64_tr_b16 v[122:123], v237 offset:7168
	v_mfma_f32_32x32x16_bf16 v[18:33], v[102:105], v[124:127], v[18:33]
	ds_read_b64_tr_b16 v[124:125], v237 offset:9216
	ds_read_b64_tr_b16 v[126:127], v237 offset:11264
	v_mfma_f32_32x32x16_bf16 v[18:33], v[98:101], v[238:241], v[18:33]
	ds_read_b64_tr_b16 v[238:239], v237 offset:13312
	ds_read_b64_tr_b16 v[240:241], v237 offset:15360
	s_waitcnt lgkmcnt(0)
	v_mfma_f32_32x32x16_bf16 v[34:49], v[110:113], v[116:119], v[34:49]
	ds_read_b64_tr_b16 v[116:117], v237 offset:1536
	ds_read_b64_tr_b16 v[118:119], v237 offset:3584
	v_mfma_f32_32x32x16_bf16 v[34:49], v[106:109], v[120:123], v[34:49]
	ds_read_b64_tr_b16 v[120:121], v237 offset:5632
	ds_read_b64_tr_b16 v[122:123], v237 offset:7680
	v_mfma_f32_32x32x16_bf16 v[34:49], v[102:105], v[124:127], v[34:49]
	ds_read_b64_tr_b16 v[124:125], v237 offset:9728
	ds_read_b64_tr_b16 v[126:127], v237 offset:11776
	v_mfma_f32_32x32x16_bf16 v[34:49], v[98:101], v[238:241], v[34:49]
	ds_read_b64_tr_b16 v[238:239], v237 offset:13824
	ds_read_b64_tr_b16 v[240:241], v237 offset:15872
	s_waitcnt lgkmcnt(0)
	v_mfma_f32_32x32x16_bf16 v[50:65], v[110:113], v[116:119], v[50:65]
	s_add_i32 s14, s14, 1
	s_cmp_eq_u32 s23, s14
	v_mfma_f32_32x32x16_bf16 v[50:65], v[106:109], v[120:123], v[50:65]
	s_waitcnt vmcnt(0)
	v_mfma_f32_32x32x16_bf16 v[50:65], v[102:105], v[124:127], v[50:65]
	s_barrier
	v_mfma_f32_32x32x16_bf16 v[50:65], v[98:101], v[238:241], v[50:65]
	s_cbranch_scc1 .LBB0_295
	v_mov_b32_e32 v202, v114
	s_branch .Lgu_a286
.Lgu_a294:
	v_max_f32_e32 v66, v82, v82
	v_max_f32_e32 v66, 0, v66
	v_exp_f32_e64 v195, -v66
	v_add_f32_e32 v203, v203, v66
	v_xor_b32_e32 v82, 0x80000000, v203
	v_pk_add_f32 v[114:115], v[114:115], v[66:67] op_sel_hi:[1,0] neg_lo:[0,1] neg_hi:[0,1]
	v_pk_add_f32 v[98:99], v[98:99], v[66:67] op_sel_hi:[1,0] neg_lo:[0,1] neg_hi:[0,1]
	v_pk_add_f32 v[116:117], v[116:117], v[66:67] op_sel_hi:[1,0] neg_lo:[0,1] neg_hi:[0,1]
	v_pk_add_f32 v[100:101], v[100:101], v[66:67] op_sel_hi:[1,0] neg_lo:[0,1] neg_hi:[0,1]
	v_pk_add_f32 v[118:119], v[118:119], v[66:67] op_sel_hi:[1,0] neg_lo:[0,1] neg_hi:[0,1]
	v_pk_add_f32 v[102:103], v[102:103], v[66:67] op_sel_hi:[1,0] neg_lo:[0,1] neg_hi:[0,1]
	v_pk_add_f32 v[120:121], v[120:121], v[66:67] op_sel_hi:[1,0] neg_lo:[0,1] neg_hi:[0,1]
	v_pk_add_f32 v[104:105], v[104:105], v[66:67] op_sel_hi:[1,0] neg_lo:[0,1] neg_hi:[0,1]
	v_pk_add_f32 v[122:123], v[122:123], v[66:67] op_sel_hi:[1,0] neg_lo:[0,1] neg_hi:[0,1]
	v_pk_add_f32 v[106:107], v[106:107], v[66:67] op_sel_hi:[1,0] neg_lo:[0,1] neg_hi:[0,1]
	v_pk_add_f32 v[124:125], v[124:125], v[66:67] op_sel_hi:[1,0] neg_lo:[0,1] neg_hi:[0,1]
	v_pk_add_f32 v[108:109], v[108:109], v[66:67] op_sel_hi:[1,0] neg_lo:[0,1] neg_hi:[0,1]
	v_pk_add_f32 v[126:127], v[126:127], v[66:67] op_sel_hi:[1,0] neg_lo:[0,1] neg_hi:[0,1]
	v_pk_add_f32 v[110:111], v[110:111], v[66:67] op_sel_hi:[1,0] neg_lo:[0,1] neg_hi:[0,1]
	v_pk_add_f32 v[128:129], v[128:129], v[66:67] op_sel_hi:[1,0] neg_lo:[0,1] neg_hi:[0,1]
	v_pk_add_f32 v[112:113], v[112:113], v[66:67] op_sel_hi:[1,0] neg_lo:[0,1] neg_hi:[0,1]
	v_mov_b32_e32 v83, v82
	v_mov_b32_e32 v84, v82
	v_mov_b32_e32 v85, v82
	v_mov_b32_e32 v86, v82
	v_mov_b32_e32 v87, v82
	v_mov_b32_e32 v88, v82
	v_mov_b32_e32 v89, v82
	v_mov_b32_e32 v90, v82
	v_mov_b32_e32 v91, v82
	v_mov_b32_e32 v92, v82
	v_mov_b32_e32 v93, v82
	v_mov_b32_e32 v94, v82
	v_mov_b32_e32 v95, v82
	v_mov_b32_e32 v96, v82
	v_mov_b32_e32 v97, v82
	v_mov_b32_e32 v66, v82
	v_mov_b32_e32 v67, v82
	v_mov_b32_e32 v68, v82
	v_mov_b32_e32 v69, v82
	v_mov_b32_e32 v70, v82
	v_mov_b32_e32 v71, v82
	v_mov_b32_e32 v72, v82
	v_mov_b32_e32 v73, v82
	v_mov_b32_e32 v74, v82
	v_mov_b32_e32 v75, v82
	v_mov_b32_e32 v76, v82
	v_mov_b32_e32 v77, v82
	v_mov_b32_e32 v78, v82
	v_mov_b32_e32 v79, v82
	v_mov_b32_e32 v80, v82
	v_mov_b32_e32 v81, v82
	s_branch .Lgu_a288
.Lgu_b294:
	v_max_f32_e32 v66, v82, v82
	v_max_f32_e32 v66, 0, v66
	v_exp_f32_e64 v195, -v66
	v_add_f32_e32 v203, v203, v66
	v_xor_b32_e32 v82, 0x80000000, v203
	v_pk_add_f32 v[114:115], v[114:115], v[66:67] op_sel_hi:[1,0] neg_lo:[0,1] neg_hi:[0,1]
	v_pk_add_f32 v[98:99], v[98:99], v[66:67] op_sel_hi:[1,0] neg_lo:[0,1] neg_hi:[0,1]
	v_pk_add_f32 v[116:117], v[116:117], v[66:67] op_sel_hi:[1,0] neg_lo:[0,1] neg_hi:[0,1]
	v_pk_add_f32 v[100:101], v[100:101], v[66:67] op_sel_hi:[1,0] neg_lo:[0,1] neg_hi:[0,1]
	v_pk_add_f32 v[118:119], v[118:119], v[66:67] op_sel_hi:[1,0] neg_lo:[0,1] neg_hi:[0,1]
	v_pk_add_f32 v[102:103], v[102:103], v[66:67] op_sel_hi:[1,0] neg_lo:[0,1] neg_hi:[0,1]
	v_pk_add_f32 v[120:121], v[120:121], v[66:67] op_sel_hi:[1,0] neg_lo:[0,1] neg_hi:[0,1]
	v_pk_add_f32 v[104:105], v[104:105], v[66:67] op_sel_hi:[1,0] neg_lo:[0,1] neg_hi:[0,1]
	v_pk_add_f32 v[122:123], v[122:123], v[66:67] op_sel_hi:[1,0] neg_lo:[0,1] neg_hi:[0,1]
	v_pk_add_f32 v[106:107], v[106:107], v[66:67] op_sel_hi:[1,0] neg_lo:[0,1] neg_hi:[0,1]
	v_pk_add_f32 v[124:125], v[124:125], v[66:67] op_sel_hi:[1,0] neg_lo:[0,1] neg_hi:[0,1]
	v_pk_add_f32 v[108:109], v[108:109], v[66:67] op_sel_hi:[1,0] neg_lo:[0,1] neg_hi:[0,1]
	v_pk_add_f32 v[126:127], v[126:127], v[66:67] op_sel_hi:[1,0] neg_lo:[0,1] neg_hi:[0,1]
	v_pk_add_f32 v[110:111], v[110:111], v[66:67] op_sel_hi:[1,0] neg_lo:[0,1] neg_hi:[0,1]
	v_pk_add_f32 v[128:129], v[128:129], v[66:67] op_sel_hi:[1,0] neg_lo:[0,1] neg_hi:[0,1]
	v_pk_add_f32 v[112:113], v[112:113], v[66:67] op_sel_hi:[1,0] neg_lo:[0,1] neg_hi:[0,1]
	v_mov_b32_e32 v83, v82
	v_mov_b32_e32 v84, v82
	v_mov_b32_e32 v85, v82
	v_mov_b32_e32 v86, v82
	v_mov_b32_e32 v87, v82
	v_mov_b32_e32 v88, v82
	v_mov_b32_e32 v89, v82
	v_mov_b32_e32 v90, v82
	v_mov_b32_e32 v91, v82
	v_mov_b32_e32 v92, v82
	v_mov_b32_e32 v93, v82
	v_mov_b32_e32 v94, v82
	v_mov_b32_e32 v95, v82
	v_mov_b32_e32 v96, v82
	v_mov_b32_e32 v97, v82
	v_mov_b32_e32 v66, v82
	v_mov_b32_e32 v67, v82
	v_mov_b32_e32 v68, v82
	v_mov_b32_e32 v69, v82
	v_mov_b32_e32 v70, v82
	v_mov_b32_e32 v71, v82
	v_mov_b32_e32 v72, v82
	v_mov_b32_e32 v73, v82
	v_mov_b32_e32 v74, v82
	v_mov_b32_e32 v75, v82
	v_mov_b32_e32 v76, v82
	v_mov_b32_e32 v77, v82
	v_mov_b32_e32 v78, v82
	v_mov_b32_e32 v79, v82
	v_mov_b32_e32 v80, v82
	v_mov_b32_e32 v81, v82
	s_branch .Lgu_b288
